# gla passes: per-sub-chunk q/k and V-tile loads issued as one batch behind an explicit counted wait (fixes a missing wait of the previous version)
# speedup vs baseline: 1.1104x; 1.0009x over previous
.LBB0_40:
	s_or_b64 exec, exec, s[0:1]
	s_and_saveexec_b64 s[0:1], s[8:9]
	ds_write_b32 v169, v1 offset:6656
	s_or_b64 exec, exec, s[0:1]
	s_waitcnt lgkmcnt(0)
	s_barrier
	ds_read_b128 v[66:69], v168
	ds_read_b128 v[70:73], v168 offset:16
	ds_read_b128 v[74:77], v168 offset:32
	ds_read_b128 v[78:81], v168 offset:48
	s_mov_b32 s2, 0xbfb8aa3b
	s_waitcnt lgkmcnt(3)
	v_mov_b32_e32 v82, v66
	s_waitcnt lgkmcnt(2)
	v_mov_b32_e32 v83, v70
	v_mov_b32_e32 v70, v67
	s_waitcnt vmcnt(30)
	v_pk_mul_f32 v[66:67], v[100:101], v[70:71]
	v_mov_b32_e32 v70, v68
	v_pk_fma_f32 v[66:67], v[98:99], v[82:83], v[66:67]
	v_mov_b32_e32 v71, v72
	s_waitcnt vmcnt(29)
	v_pk_fma_f32 v[66:67], v[102:103], v[70:71], v[66:67]
	v_mov_b32_e32 v72, v69
	s_waitcnt vmcnt(22)
	v_pk_fma_f32 v[66:67], v[110:111], v[72:73], v[66:67]
	s_mov_b32 s33, 0x800000
	s_waitcnt vmcnt(18)
	v_add_f32_e32 v0, v165, v66
	v_add_f32_e32 v0, v0, v67
	s_waitcnt lgkmcnt(0)
	v_mov_b32_e32 v67, v78
	v_mov_b32_e32 v78, v75
	v_mov_b32_e32 v66, v74
	v_pk_mul_f32 v[68:69], v[106:107], v[78:79]
	s_mov_b32 s3, 0x3f317217
	v_pk_fma_f32 v[66:67], v[104:105], v[66:67], v[68:69]
	v_mov_b32_e32 v68, v76
	v_mov_b32_e32 v69, v80
	v_pk_fma_f32 v[66:67], v[108:109], v[68:69], v[66:67]
	v_mov_b32_e32 v80, v77
	v_pk_fma_f32 v[66:67], v[112:113], v[80:81], v[66:67]
	ds_read_b128 v[68:71], v168 offset:64
	ds_read_b128 v[72:75], v168 offset:80
	v_add_f32_e32 v0, v0, v66
	v_add_f32_e32 v0, v0, v67
	v_min_f32_e32 v66, 0, v0
	v_mul_f32_e64 v0, |v0|, s2
	v_exp_f32_e32 v0, v0
	s_mov_b32 s69, 0x7f800000
	s_waitcnt lgkmcnt(0)
	v_mov_b32_e32 v77, v72
	v_mov_b32_e32 v72, v69
	v_add_f32_e32 v0, 1.0, v0
	v_cmp_gt_f32_e32 vcc, s33, v0
	v_mov_b32_e32 v76, v68
	v_pk_mul_f32 v[68:69], v[100:101], v[72:73]
	v_cndmask_b32_e64 v67, 0, 32, vcc
	v_ldexp_f32 v0, v0, v67
	v_log_f32_e32 v0, v0
	v_pk_fma_f32 v[68:69], v[98:99], v[76:77], v[68:69]
	v_mov_b32_e32 v72, v70
	v_mov_b32_e32 v73, v74
	v_mul_f32_e32 v67, 0x3f317217, v0
	v_fma_f32 v67, v0, s3, -v67
	v_fmac_f32_e32 v67, 0x3377d1cf, v0
	v_fmac_f32_e32 v67, 0x3f317217, v0
	v_cmp_lt_f32_e64 s[0:1], |v0|, s69
	v_pk_fma_f32 v[68:69], v[102:103], v[72:73], v[68:69]
	v_mov_b32_e32 v74, v71
	v_cndmask_b32_e64 v0, v0, v67, s[0:1]
	v_cndmask_b32_e32 v67, 0, v223, vcc
	v_sub_f32_e32 v0, v0, v67
	v_sub_f32_e32 v0, v66, v0
	v_pk_fma_f32 v[68:69], v[110:111], v[74:75], v[68:69]
	v_fma_f32 v66, v0, s90, 0
	v_add_f32_e32 v0, v165, v68
	v_add_f32_e32 v0, v0, v69
	ds_read_b128 v[68:71], v168 offset:96
	ds_read_b128 v[72:75], v168 offset:112
	s_waitcnt lgkmcnt(1)
	v_mov_b32_e32 v76, v68
	s_waitcnt lgkmcnt(0)
	v_mov_b32_e32 v77, v72
	v_mov_b32_e32 v72, v69
	v_pk_mul_f32 v[68:69], v[106:107], v[72:73]
	v_mov_b32_e32 v72, v70
	v_pk_fma_f32 v[68:69], v[104:105], v[76:77], v[68:69]
	v_mov_b32_e32 v73, v74
	v_pk_fma_f32 v[68:69], v[108:109], v[72:73], v[68:69]
	v_mov_b32_e32 v74, v71
	v_pk_fma_f32 v[68:69], v[112:113], v[74:75], v[68:69]
	s_nop 0
	v_add_f32_e32 v0, v0, v68
	v_add_f32_e32 v0, v0, v69
	v_min_f32_e32 v67, 0, v0
	v_mul_f32_e64 v0, |v0|, s2
	v_exp_f32_e32 v0, v0
	s_nop 0
	v_add_f32_e32 v0, 1.0, v0
	v_cmp_gt_f32_e32 vcc, s33, v0
	s_nop 1
	v_cndmask_b32_e64 v68, 0, 32, vcc
	v_ldexp_f32 v0, v0, v68
	v_log_f32_e32 v0, v0
	s_nop 0
	v_mul_f32_e32 v68, 0x3f317217, v0
	v_fma_f32 v68, v0, s3, -v68
	v_fmac_f32_e32 v68, 0x3377d1cf, v0
	v_fmac_f32_e32 v68, 0x3f317217, v0
	v_cmp_lt_f32_e64 s[0:1], |v0|, s69
	s_nop 1
	v_cndmask_b32_e64 v0, v0, v68, s[0:1]
	v_cndmask_b32_e32 v68, 0, v223, vcc
	v_sub_f32_e32 v0, v0, v68
	ds_read_b128 v[68:71], v168 offset:128
	ds_read_b128 v[72:75], v168 offset:144
	v_sub_f32_e32 v0, v67, v0
	v_fmamk_f32 v67, v0, 0x3d800000, v66
	s_waitcnt lgkmcnt(1)
	v_mov_b32_e32 v76, v68
	s_waitcnt lgkmcnt(0)
	v_mov_b32_e32 v77, v72
	v_mov_b32_e32 v72, v69
	v_pk_mul_f32 v[68:69], v[100:101], v[72:73]
	v_mov_b32_e32 v72, v70
	v_pk_fma_f32 v[68:69], v[98:99], v[76:77], v[68:69]
	v_mov_b32_e32 v73, v74
	v_pk_fma_f32 v[68:69], v[102:103], v[72:73], v[68:69]
	v_mov_b32_e32 v74, v71
	v_pk_fma_f32 v[68:69], v[110:111], v[74:75], v[68:69]
	s_nop 0
	v_add_f32_e32 v0, v165, v68
	v_add_f32_e32 v0, v0, v69
	ds_read_b128 v[68:71], v168 offset:160
	ds_read_b128 v[72:75], v168 offset:176
	s_waitcnt lgkmcnt(1)
	v_mov_b32_e32 v76, v68
	s_waitcnt lgkmcnt(0)
	v_mov_b32_e32 v77, v72
	v_mov_b32_e32 v72, v69
	v_pk_mul_f32 v[68:69], v[106:107], v[72:73]
	v_mov_b32_e32 v72, v70
	v_pk_fma_f32 v[68:69], v[104:105], v[76:77], v[68:69]
	v_mov_b32_e32 v73, v74
	v_pk_fma_f32 v[68:69], v[108:109], v[72:73], v[68:69]
	v_mov_b32_e32 v74, v71
	v_pk_fma_f32 v[68:69], v[112:113], v[74:75], v[68:69]
	ds_read_b128 v[70:73], v168 offset:192
	ds_read_b128 v[74:77], v168 offset:208
	v_add_f32_e32 v0, v0, v68
	v_add_f32_e32 v0, v0, v69
	v_min_f32_e32 v68, 0, v0
	v_mul_f32_e64 v0, |v0|, s2
	v_exp_f32_e32 v0, v0
	s_waitcnt lgkmcnt(0)
	v_mov_b32_e32 v79, v74
	v_mov_b32_e32 v74, v71
	v_mov_b32_e32 v78, v70
	v_add_f32_e32 v0, 1.0, v0
	v_cmp_gt_f32_e32 vcc, s33, v0
	v_pk_mul_f32 v[70:71], v[100:101], v[74:75]
	v_mov_b32_e32 v74, v72
	v_cndmask_b32_e64 v69, 0, 32, vcc
	v_ldexp_f32 v0, v0, v69
	v_log_f32_e32 v0, v0
	v_pk_fma_f32 v[70:71], v[98:99], v[78:79], v[70:71]
	v_mov_b32_e32 v75, v76
	v_pk_fma_f32 v[70:71], v[102:103], v[74:75], v[70:71]
	v_mul_f32_e32 v69, 0x3f317217, v0
	v_fma_f32 v69, v0, s3, -v69
	v_fmac_f32_e32 v69, 0x3377d1cf, v0
	v_fmac_f32_e32 v69, 0x3f317217, v0
	v_cmp_lt_f32_e64 s[0:1], |v0|, s69
	v_mov_b32_e32 v76, v73
	v_pk_fma_f32 v[70:71], v[110:111], v[76:77], v[70:71]
	v_cndmask_b32_e64 v0, v0, v69, s[0:1]
	v_cndmask_b32_e32 v69, 0, v223, vcc
	v_sub_f32_e32 v0, v0, v69
	v_sub_f32_e32 v0, v68, v0
	v_fmamk_f32 v68, v0, 0x3d800000, v67
	v_add_f32_e32 v0, v165, v70
	v_add_f32_e32 v0, v0, v71
	ds_read_b128 v[70:73], v168 offset:224
	ds_read_b128 v[74:77], v168 offset:240
	s_waitcnt lgkmcnt(1)
	v_mov_b32_e32 v78, v70
	s_waitcnt lgkmcnt(0)
	v_mov_b32_e32 v79, v74
	v_mov_b32_e32 v74, v71
	v_pk_mul_f32 v[70:71], v[106:107], v[74:75]
	v_mov_b32_e32 v74, v72
	v_pk_fma_f32 v[70:71], v[104:105], v[78:79], v[70:71]
	v_mov_b32_e32 v75, v76
	v_pk_fma_f32 v[70:71], v[108:109], v[74:75], v[70:71]
	v_mov_b32_e32 v76, v73
	v_pk_fma_f32 v[70:71], v[112:113], v[76:77], v[70:71]
	s_nop 0
	v_add_f32_e32 v0, v0, v70
	v_add_f32_e32 v0, v0, v71
	v_min_f32_e32 v69, 0, v0
	v_mul_f32_e64 v0, |v0|, s2
	v_exp_f32_e32 v0, v0
	s_nop 0
	v_add_f32_e32 v0, 1.0, v0
	v_cmp_gt_f32_e32 vcc, s33, v0
	s_nop 1
	v_cndmask_b32_e64 v70, 0, 32, vcc
	v_ldexp_f32 v0, v0, v70
	v_log_f32_e32 v0, v0
	s_nop 0
	v_mul_f32_e32 v70, 0x3f317217, v0
	v_fma_f32 v70, v0, s3, -v70
	v_fmac_f32_e32 v70, 0x3377d1cf, v0
	v_fmac_f32_e32 v70, 0x3f317217, v0
	v_cmp_lt_f32_e64 s[0:1], |v0|, s69
	s_nop 1
	v_cndmask_b32_e64 v0, v0, v70, s[0:1]
	v_cndmask_b32_e32 v70, 0, v223, vcc
	v_sub_f32_e32 v0, v0, v70
	ds_read_b128 v[70:73], v168 offset:256
	ds_read_b128 v[74:77], v168 offset:272
	v_sub_f32_e32 v0, v69, v0
	v_fmamk_f32 v69, v0, 0x3d800000, v68
	s_waitcnt lgkmcnt(1)
	v_mov_b32_e32 v78, v70
	s_waitcnt lgkmcnt(0)
	v_mov_b32_e32 v79, v74
	v_mov_b32_e32 v74, v71
	v_pk_mul_f32 v[70:71], v[100:101], v[74:75]
	v_mov_b32_e32 v74, v72
	v_pk_fma_f32 v[70:71], v[98:99], v[78:79], v[70:71]
	v_mov_b32_e32 v75, v76
	v_pk_fma_f32 v[70:71], v[102:103], v[74:75], v[70:71]
	v_mov_b32_e32 v76, v73
	v_pk_fma_f32 v[70:71], v[110:111], v[76:77], v[70:71]
	s_nop 0
	v_add_f32_e32 v0, v165, v70
	v_add_f32_e32 v0, v0, v71
	ds_read_b128 v[70:73], v168 offset:288
	ds_read_b128 v[74:77], v168 offset:304
	s_waitcnt lgkmcnt(1)
	v_mov_b32_e32 v78, v70
	s_waitcnt lgkmcnt(0)
	v_mov_b32_e32 v79, v74
	v_mov_b32_e32 v74, v71
	v_pk_mul_f32 v[70:71], v[106:107], v[74:75]
	v_mov_b32_e32 v74, v72
	v_pk_fma_f32 v[70:71], v[104:105], v[78:79], v[70:71]
	v_mov_b32_e32 v75, v76
	v_pk_fma_f32 v[70:71], v[108:109], v[74:75], v[70:71]
	v_mov_b32_e32 v76, v73
	v_pk_fma_f32 v[70:71], v[112:113], v[76:77], v[70:71]
	ds_read_b128 v[72:75], v168 offset:320
	ds_read_b128 v[76:79], v168 offset:336
	v_add_f32_e32 v0, v0, v70
	v_add_f32_e32 v0, v0, v71
	v_min_f32_e32 v70, 0, v0
	v_mul_f32_e64 v0, |v0|, s2
	v_exp_f32_e32 v0, v0
	s_waitcnt lgkmcnt(0)
	v_mov_b32_e32 v81, v76
	v_mov_b32_e32 v76, v73
	v_mov_b32_e32 v80, v72
	v_add_f32_e32 v0, 1.0, v0
	v_cmp_gt_f32_e32 vcc, s33, v0
	v_pk_mul_f32 v[72:73], v[100:101], v[76:77]
	v_mov_b32_e32 v76, v74
	v_cndmask_b32_e64 v71, 0, 32, vcc
	v_ldexp_f32 v0, v0, v71
	v_log_f32_e32 v0, v0
	v_pk_fma_f32 v[72:73], v[98:99], v[80:81], v[72:73]
	v_mov_b32_e32 v77, v78
	v_pk_fma_f32 v[72:73], v[102:103], v[76:77], v[72:73]
	v_mul_f32_e32 v71, 0x3f317217, v0
	v_fma_f32 v71, v0, s3, -v71
	v_fmac_f32_e32 v71, 0x3377d1cf, v0
	v_fmac_f32_e32 v71, 0x3f317217, v0
	v_cmp_lt_f32_e64 s[0:1], |v0|, s69
	v_mov_b32_e32 v78, v75
	v_pk_fma_f32 v[72:73], v[110:111], v[78:79], v[72:73]
	v_cndmask_b32_e64 v0, v0, v71, s[0:1]
	v_cndmask_b32_e32 v71, 0, v223, vcc
	v_sub_f32_e32 v0, v0, v71
	v_sub_f32_e32 v0, v70, v0
	v_fmamk_f32 v70, v0, 0x3d800000, v69
	v_add_f32_e32 v0, v165, v72
	v_add_f32_e32 v0, v0, v73
	ds_read_b128 v[72:75], v168 offset:352
	ds_read_b128 v[76:79], v168 offset:368
	s_waitcnt lgkmcnt(1)
	v_mov_b32_e32 v80, v72
	s_waitcnt lgkmcnt(0)
	v_mov_b32_e32 v81, v76
	v_mov_b32_e32 v76, v73
	v_pk_mul_f32 v[72:73], v[106:107], v[76:77]
	v_mov_b32_e32 v76, v74
	v_pk_fma_f32 v[72:73], v[104:105], v[80:81], v[72:73]
	v_mov_b32_e32 v77, v78
	v_pk_fma_f32 v[72:73], v[108:109], v[76:77], v[72:73]
	v_mov_b32_e32 v78, v75
	v_pk_fma_f32 v[72:73], v[112:113], v[78:79], v[72:73]
	s_nop 0
	v_add_f32_e32 v0, v0, v72
	v_add_f32_e32 v0, v0, v73
	v_min_f32_e32 v71, 0, v0
	v_mul_f32_e64 v0, |v0|, s2
	v_exp_f32_e32 v0, v0
	s_nop 0
	v_add_f32_e32 v0, 1.0, v0
	v_cmp_gt_f32_e32 vcc, s33, v0
	s_nop 1
	v_cndmask_b32_e64 v72, 0, 32, vcc
	v_ldexp_f32 v0, v0, v72
	v_log_f32_e32 v0, v0
	s_nop 0
	v_mul_f32_e32 v72, 0x3f317217, v0
	v_fma_f32 v72, v0, s3, -v72
	v_fmac_f32_e32 v72, 0x3377d1cf, v0
	v_fmac_f32_e32 v72, 0x3f317217, v0
	v_cmp_lt_f32_e64 s[0:1], |v0|, s69
	s_nop 1
	v_cndmask_b32_e64 v0, v0, v72, s[0:1]
	v_cndmask_b32_e32 v72, 0, v223, vcc
	v_sub_f32_e32 v0, v0, v72
	ds_read_b128 v[72:75], v168 offset:384
	ds_read_b128 v[76:79], v168 offset:400
	v_sub_f32_e32 v0, v71, v0
	v_fmamk_f32 v71, v0, 0x3d800000, v70
	s_waitcnt lgkmcnt(1)
	v_mov_b32_e32 v80, v72
	s_waitcnt lgkmcnt(0)
	v_mov_b32_e32 v81, v76
	v_mov_b32_e32 v76, v73
	v_pk_mul_f32 v[72:73], v[100:101], v[76:77]
	v_mov_b32_e32 v76, v74
	v_pk_fma_f32 v[72:73], v[98:99], v[80:81], v[72:73]
	v_mov_b32_e32 v77, v78
	v_pk_fma_f32 v[72:73], v[102:103], v[76:77], v[72:73]
	v_mov_b32_e32 v78, v75
	v_pk_fma_f32 v[72:73], v[110:111], v[78:79], v[72:73]
	s_nop 0
	v_add_f32_e32 v0, v165, v72
	v_add_f32_e32 v0, v0, v73
	ds_read_b128 v[72:75], v168 offset:416
	ds_read_b128 v[76:79], v168 offset:432
	s_waitcnt lgkmcnt(1)
	v_mov_b32_e32 v80, v72
	s_waitcnt lgkmcnt(0)
	v_mov_b32_e32 v81, v76
	v_mov_b32_e32 v76, v73
	v_pk_mul_f32 v[72:73], v[106:107], v[76:77]
	v_mov_b32_e32 v76, v74
	v_pk_fma_f32 v[72:73], v[104:105], v[80:81], v[72:73]
	v_mov_b32_e32 v77, v78
	v_pk_fma_f32 v[72:73], v[108:109], v[76:77], v[72:73]
	v_mov_b32_e32 v78, v75
	v_pk_fma_f32 v[72:73], v[112:113], v[78:79], v[72:73]
	ds_read_b128 v[74:77], v168 offset:448
	ds_read_b128 v[78:81], v168 offset:464
	v_add_f32_e32 v0, v0, v72
	v_add_f32_e32 v0, v0, v73
	v_min_f32_e32 v72, 0, v0
	v_mul_f32_e64 v0, |v0|, s2
	v_exp_f32_e32 v0, v0
	s_waitcnt lgkmcnt(0)
	v_mov_b32_e32 v83, v78
	v_mov_b32_e32 v78, v75
	v_mov_b32_e32 v82, v74
	v_add_f32_e32 v0, 1.0, v0
	v_cmp_gt_f32_e32 vcc, s33, v0
	v_pk_mul_f32 v[74:75], v[100:101], v[78:79]
	v_mov_b32_e32 v78, v76
	v_cndmask_b32_e64 v73, 0, 32, vcc
	v_ldexp_f32 v0, v0, v73
	v_log_f32_e32 v0, v0
	v_pk_fma_f32 v[74:75], v[98:99], v[82:83], v[74:75]
	v_mov_b32_e32 v79, v80
	v_pk_fma_f32 v[74:75], v[102:103], v[78:79], v[74:75]
	v_mul_f32_e32 v73, 0x3f317217, v0
	v_fma_f32 v73, v0, s3, -v73
	v_fmac_f32_e32 v73, 0x3377d1cf, v0
	v_fmac_f32_e32 v73, 0x3f317217, v0
	v_cmp_lt_f32_e64 s[0:1], |v0|, s69
	v_mov_b32_e32 v80, v77
	v_pk_fma_f32 v[74:75], v[110:111], v[80:81], v[74:75]
	v_cndmask_b32_e64 v0, v0, v73, s[0:1]
	v_cndmask_b32_e32 v73, 0, v223, vcc
	v_sub_f32_e32 v0, v0, v73
	v_sub_f32_e32 v0, v72, v0
	v_fmamk_f32 v73, v0, 0x3d800000, v71
	v_add_f32_e32 v0, v165, v74
	v_add_f32_e32 v0, v0, v75
	ds_read_b128 v[74:77], v168 offset:480
	ds_read_b128 v[78:81], v168 offset:496
	s_waitcnt lgkmcnt(1)
	v_mov_b32_e32 v82, v74
	s_waitcnt lgkmcnt(0)
	v_mov_b32_e32 v83, v78
	v_mov_b32_e32 v78, v75
	v_pk_mul_f32 v[74:75], v[106:107], v[78:79]
	v_mov_b32_e32 v78, v76
	v_pk_fma_f32 v[74:75], v[104:105], v[82:83], v[74:75]
	v_mov_b32_e32 v79, v80
	v_pk_fma_f32 v[74:75], v[108:109], v[78:79], v[74:75]
	v_mov_b32_e32 v80, v77
	v_pk_fma_f32 v[74:75], v[112:113], v[80:81], v[74:75]
	ds_read_b128 v[76:79], v168 offset:512
	ds_read_b128 v[80:83], v168 offset:528
	v_add_f32_e32 v0, v0, v74
	v_add_f32_e32 v0, v0, v75
	v_min_f32_e32 v72, 0, v0
	v_mul_f32_e64 v0, |v0|, s2
	v_exp_f32_e32 v0, v0
	s_waitcnt lgkmcnt(0)
	v_mov_b32_e32 v85, v80
	v_mov_b32_e32 v80, v77
	v_mov_b32_e32 v84, v76
	v_add_f32_e32 v0, 1.0, v0
	v_cmp_gt_f32_e32 vcc, s33, v0
	v_pk_mul_f32 v[76:77], v[100:101], v[80:81]
	v_mov_b32_e32 v80, v78
	v_cndmask_b32_e64 v74, 0, 32, vcc
	v_ldexp_f32 v0, v0, v74
	v_log_f32_e32 v0, v0
	v_pk_fma_f32 v[76:77], v[98:99], v[84:85], v[76:77]
	v_mov_b32_e32 v81, v82
	v_pk_fma_f32 v[76:77], v[102:103], v[80:81], v[76:77]
	v_mul_f32_e32 v74, 0x3f317217, v0
	v_fma_f32 v74, v0, s3, -v74
	v_fmac_f32_e32 v74, 0x3377d1cf, v0
	v_fmac_f32_e32 v74, 0x3f317217, v0
	v_cmp_lt_f32_e64 s[0:1], |v0|, s69
	v_mov_b32_e32 v82, v79
	v_pk_fma_f32 v[76:77], v[110:111], v[82:83], v[76:77]
	v_cndmask_b32_e64 v0, v0, v74, s[0:1]
	v_cndmask_b32_e32 v74, 0, v223, vcc
	v_sub_f32_e32 v0, v0, v74
	v_sub_f32_e32 v0, v72, v0
	v_fmamk_f32 v75, v0, 0x3d800000, v73
	v_add_f32_e32 v0, v165, v76
	v_add_f32_e32 v0, v0, v77
	ds_read_b128 v[76:79], v168 offset:544
	ds_read_b128 v[80:83], v168 offset:560
	s_waitcnt lgkmcnt(1)
	v_mov_b32_e32 v84, v76
	s_waitcnt lgkmcnt(0)
	v_mov_b32_e32 v85, v80
	v_mov_b32_e32 v80, v77
	v_pk_mul_f32 v[76:77], v[106:107], v[80:81]
	v_mov_b32_e32 v80, v78
	v_pk_fma_f32 v[76:77], v[104:105], v[84:85], v[76:77]
	v_mov_b32_e32 v81, v82
	v_pk_fma_f32 v[76:77], v[108:109], v[80:81], v[76:77]
	v_mov_b32_e32 v82, v79
	v_pk_fma_f32 v[76:77], v[112:113], v[82:83], v[76:77]
	ds_read_b128 v[78:81], v168 offset:576
	ds_read_b128 v[82:85], v168 offset:592
	v_add_f32_e32 v0, v0, v76
	v_add_f32_e32 v0, v0, v77
	v_min_f32_e32 v72, 0, v0
	v_mul_f32_e64 v0, |v0|, s2
	v_exp_f32_e32 v0, v0
	s_waitcnt lgkmcnt(0)
	v_mov_b32_e32 v87, v82
	v_mov_b32_e32 v82, v79
	v_mov_b32_e32 v86, v78
	v_add_f32_e32 v0, 1.0, v0
	v_cmp_gt_f32_e32 vcc, s33, v0
	v_pk_mul_f32 v[78:79], v[100:101], v[82:83]
	v_mov_b32_e32 v82, v80
	v_cndmask_b32_e64 v74, 0, 32, vcc
	v_ldexp_f32 v0, v0, v74
	v_log_f32_e32 v0, v0
	v_pk_fma_f32 v[78:79], v[98:99], v[86:87], v[78:79]
	v_mov_b32_e32 v83, v84
	v_pk_fma_f32 v[78:79], v[102:103], v[82:83], v[78:79]
	v_mul_f32_e32 v74, 0x3f317217, v0
	v_fma_f32 v74, v0, s3, -v74
	v_fmac_f32_e32 v74, 0x3377d1cf, v0
	v_fmac_f32_e32 v74, 0x3f317217, v0
	v_cmp_lt_f32_e64 s[0:1], |v0|, s69
	v_mov_b32_e32 v84, v81
	v_pk_fma_f32 v[78:79], v[110:111], v[84:85], v[78:79]
	v_cndmask_b32_e64 v0, v0, v74, s[0:1]
	v_cndmask_b32_e32 v74, 0, v223, vcc
	v_sub_f32_e32 v0, v0, v74
	v_sub_f32_e32 v0, v72, v0
	v_fmamk_f32 v76, v0, 0x3d800000, v75
	v_add_f32_e32 v0, v165, v78
	v_add_f32_e32 v0, v0, v79
	ds_read_b128 v[78:81], v168 offset:608
	ds_read_b128 v[82:85], v168 offset:624
	s_waitcnt lgkmcnt(1)
	v_mov_b32_e32 v86, v78
	s_waitcnt lgkmcnt(0)
	v_mov_b32_e32 v87, v82
	v_mov_b32_e32 v82, v79
	v_pk_mul_f32 v[78:79], v[106:107], v[82:83]
	v_mov_b32_e32 v82, v80
	v_pk_fma_f32 v[78:79], v[104:105], v[86:87], v[78:79]
	v_mov_b32_e32 v83, v84
	v_pk_fma_f32 v[78:79], v[108:109], v[82:83], v[78:79]
	v_mov_b32_e32 v84, v81
	v_pk_fma_f32 v[78:79], v[112:113], v[84:85], v[78:79]
	s_nop 0
	v_add_f32_e32 v0, v0, v78
	v_add_f32_e32 v0, v0, v79
	v_min_f32_e32 v72, 0, v0
	v_mul_f32_e64 v0, |v0|, s2
	v_exp_f32_e32 v0, v0
	ds_read_b128 v[78:81], v168 offset:640
	ds_read_b128 v[82:85], v168 offset:656
	v_add_f32_e32 v0, 1.0, v0
	v_cmp_gt_f32_e32 vcc, s33, v0
	s_waitcnt lgkmcnt(0)
	v_mov_b32_e32 v87, v82
	v_mov_b32_e32 v82, v79
	v_cndmask_b32_e64 v74, 0, 32, vcc
	v_ldexp_f32 v0, v0, v74
	v_log_f32_e32 v0, v0
	v_mov_b32_e32 v86, v78
	v_pk_mul_f32 v[78:79], v[100:101], v[82:83]
	v_mov_b32_e32 v82, v80
	v_mul_f32_e32 v74, 0x3f317217, v0
	v_fma_f32 v74, v0, s3, -v74
	v_fmac_f32_e32 v74, 0x3377d1cf, v0
	v_fmac_f32_e32 v74, 0x3f317217, v0
	v_cmp_lt_f32_e64 s[0:1], |v0|, s69
	v_pk_fma_f32 v[78:79], v[98:99], v[86:87], v[78:79]
	v_mov_b32_e32 v83, v84
	v_cndmask_b32_e64 v0, v0, v74, s[0:1]
	v_cndmask_b32_e32 v74, 0, v223, vcc
	v_sub_f32_e32 v0, v0, v74
	v_pk_fma_f32 v[78:79], v[102:103], v[82:83], v[78:79]
	v_mov_b32_e32 v84, v81
	v_sub_f32_e32 v0, v72, v0
	v_pk_fma_f32 v[78:79], v[110:111], v[84:85], v[78:79]
	v_fmamk_f32 v72, v0, 0x3d800000, v76
	v_add_f32_e32 v0, v165, v78
	v_add_f32_e32 v0, v0, v79
	ds_read_b128 v[78:81], v168 offset:672
	ds_read_b128 v[82:85], v168 offset:688
	s_waitcnt lgkmcnt(1)
	v_mov_b32_e32 v86, v78
	s_waitcnt lgkmcnt(0)
	v_mov_b32_e32 v87, v82
	v_mov_b32_e32 v82, v79
	v_pk_mul_f32 v[78:79], v[106:107], v[82:83]
	v_mov_b32_e32 v82, v80
	v_pk_fma_f32 v[78:79], v[104:105], v[86:87], v[78:79]
	v_mov_b32_e32 v83, v84
	v_pk_fma_f32 v[78:79], v[108:109], v[82:83], v[78:79]
	v_mov_b32_e32 v84, v81
	v_pk_fma_f32 v[78:79], v[112:113], v[84:85], v[78:79]
	s_nop 0
	v_add_f32_e32 v0, v0, v78
	v_add_f32_e32 v0, v0, v79
	v_min_f32_e32 v74, 0, v0
	v_mul_f32_e64 v0, |v0|, s2
	v_exp_f32_e32 v0, v0
	ds_read_b128 v[78:81], v168 offset:704
	ds_read_b128 v[82:85], v168 offset:720
	v_add_f32_e32 v0, 1.0, v0
	v_cmp_gt_f32_e32 vcc, s33, v0
	s_waitcnt lgkmcnt(0)
	v_mov_b32_e32 v87, v82
	v_mov_b32_e32 v82, v79
	v_cndmask_b32_e64 v77, 0, 32, vcc
	v_ldexp_f32 v0, v0, v77
	v_log_f32_e32 v0, v0
	v_mov_b32_e32 v86, v78
	v_pk_mul_f32 v[78:79], v[100:101], v[82:83]
	v_mov_b32_e32 v82, v80
	v_mul_f32_e32 v77, 0x3f317217, v0
	v_fma_f32 v77, v0, s3, -v77
	v_fmac_f32_e32 v77, 0x3377d1cf, v0
	v_fmac_f32_e32 v77, 0x3f317217, v0
	v_cmp_lt_f32_e64 s[0:1], |v0|, s69
	v_pk_fma_f32 v[78:79], v[98:99], v[86:87], v[78:79]
	v_mov_b32_e32 v83, v84
	v_cndmask_b32_e64 v0, v0, v77, s[0:1]
	v_cndmask_b32_e32 v77, 0, v223, vcc
	v_sub_f32_e32 v0, v0, v77
	v_pk_fma_f32 v[78:79], v[102:103], v[82:83], v[78:79]
	v_mov_b32_e32 v84, v81
	v_sub_f32_e32 v0, v74, v0
	v_pk_fma_f32 v[78:79], v[110:111], v[84:85], v[78:79]
	v_fmamk_f32 v74, v0, 0x3d800000, v72
	v_add_f32_e32 v0, v165, v78
	v_add_f32_e32 v0, v0, v79
	ds_read_b128 v[78:81], v168 offset:736
	ds_read_b128 v[82:85], v168 offset:752
	s_waitcnt lgkmcnt(1)
	v_mov_b32_e32 v86, v78
	s_waitcnt lgkmcnt(0)
	v_mov_b32_e32 v87, v82
	v_mov_b32_e32 v82, v79
	v_pk_mul_f32 v[78:79], v[106:107], v[82:83]
	v_mov_b32_e32 v82, v80
	v_pk_fma_f32 v[78:79], v[104:105], v[86:87], v[78:79]
	v_mov_b32_e32 v83, v84
	v_pk_fma_f32 v[78:79], v[108:109], v[82:83], v[78:79]
	v_mov_b32_e32 v84, v81
	v_pk_fma_f32 v[78:79], v[112:113], v[84:85], v[78:79]
	s_nop 0
	v_add_f32_e32 v0, v0, v78
	v_add_f32_e32 v0, v0, v79
	v_min_f32_e32 v77, 0, v0
	v_mul_f32_e64 v0, |v0|, s2
	v_exp_f32_e32 v0, v0
	s_nop 0
	v_add_f32_e32 v0, 1.0, v0
	v_cmp_gt_f32_e32 vcc, s33, v0
	s_nop 1
	v_cndmask_b32_e64 v78, 0, 32, vcc
	v_ldexp_f32 v0, v0, v78
	v_log_f32_e32 v0, v0
	s_nop 0
	v_mul_f32_e32 v78, 0x3f317217, v0
	v_fma_f32 v78, v0, s3, -v78
	v_fmac_f32_e32 v78, 0x3377d1cf, v0
	v_fmac_f32_e32 v78, 0x3f317217, v0
	v_cmp_lt_f32_e64 s[0:1], |v0|, s69
	s_nop 1
	v_cndmask_b32_e64 v0, v0, v78, s[0:1]
	v_cndmask_b32_e32 v78, 0, v223, vcc
	v_sub_f32_e32 v0, v0, v78
	ds_read_b128 v[78:81], v168 offset:768
	ds_read_b128 v[82:85], v168 offset:784
	v_sub_f32_e32 v0, v77, v0
	v_fmamk_f32 v77, v0, 0x3d800000, v74
	s_waitcnt lgkmcnt(1)
	v_mov_b32_e32 v86, v78
	s_waitcnt lgkmcnt(0)
	v_mov_b32_e32 v87, v82
	v_mov_b32_e32 v82, v79
	v_pk_mul_f32 v[78:79], v[100:101], v[82:83]
	v_mov_b32_e32 v82, v80
	v_pk_fma_f32 v[78:79], v[98:99], v[86:87], v[78:79]
	v_mov_b32_e32 v83, v84
	v_pk_fma_f32 v[78:79], v[102:103], v[82:83], v[78:79]
	v_mov_b32_e32 v84, v81
	v_pk_fma_f32 v[78:79], v[110:111], v[84:85], v[78:79]
	s_nop 0
	v_add_f32_e32 v0, v165, v78
	v_add_f32_e32 v0, v0, v79
	ds_read_b128 v[78:81], v168 offset:800
	ds_read_b128 v[82:85], v168 offset:816
	s_waitcnt lgkmcnt(1)
	v_mov_b32_e32 v86, v78
	s_waitcnt lgkmcnt(0)
	v_mov_b32_e32 v87, v82
	v_mov_b32_e32 v82, v79
	v_pk_mul_f32 v[78:79], v[106:107], v[82:83]
	v_mov_b32_e32 v82, v80
	v_pk_fma_f32 v[78:79], v[104:105], v[86:87], v[78:79]
	v_mov_b32_e32 v83, v84
	v_pk_fma_f32 v[78:79], v[108:109], v[82:83], v[78:79]
	v_mov_b32_e32 v84, v81
	v_pk_fma_f32 v[78:79], v[112:113], v[84:85], v[78:79]
	ds_read_b128 v[80:83], v168 offset:832
	ds_read_b128 v[84:87], v168 offset:848
	v_add_f32_e32 v0, v0, v78
	v_add_f32_e32 v0, v0, v79
	v_min_f32_e32 v78, 0, v0
	v_mul_f32_e64 v0, |v0|, s2
	v_exp_f32_e32 v0, v0
	s_waitcnt lgkmcnt(0)
	v_mov_b32_e32 v89, v84
	v_mov_b32_e32 v84, v81
	v_mov_b32_e32 v88, v80
	v_add_f32_e32 v0, 1.0, v0
	v_cmp_gt_f32_e32 vcc, s33, v0
	v_pk_mul_f32 v[80:81], v[100:101], v[84:85]
	v_mov_b32_e32 v84, v82
	v_cndmask_b32_e64 v79, 0, 32, vcc
	v_ldexp_f32 v0, v0, v79
	v_log_f32_e32 v0, v0
	v_pk_fma_f32 v[80:81], v[98:99], v[88:89], v[80:81]
	v_mov_b32_e32 v85, v86
	v_pk_fma_f32 v[80:81], v[102:103], v[84:85], v[80:81]
	v_mul_f32_e32 v79, 0x3f317217, v0
	v_fma_f32 v79, v0, s3, -v79
	v_fmac_f32_e32 v79, 0x3377d1cf, v0
	v_fmac_f32_e32 v79, 0x3f317217, v0
	v_cmp_lt_f32_e64 s[0:1], |v0|, s69
	v_mov_b32_e32 v86, v83
	v_pk_fma_f32 v[80:81], v[110:111], v[86:87], v[80:81]
	v_cndmask_b32_e64 v0, v0, v79, s[0:1]
	v_cndmask_b32_e32 v79, 0, v223, vcc
	v_sub_f32_e32 v0, v0, v79
	v_sub_f32_e32 v0, v78, v0
	v_fmamk_f32 v78, v0, 0x3d800000, v77
	v_add_f32_e32 v0, v165, v80
	v_add_f32_e32 v0, v0, v81
	ds_read_b128 v[80:83], v168 offset:864
	ds_read_b128 v[84:87], v168 offset:880
	s_waitcnt lgkmcnt(1)
	v_mov_b32_e32 v88, v80
	s_waitcnt lgkmcnt(0)
	v_mov_b32_e32 v89, v84
	v_mov_b32_e32 v84, v81
	v_pk_mul_f32 v[80:81], v[106:107], v[84:85]
	v_mov_b32_e32 v84, v82
	v_pk_fma_f32 v[80:81], v[104:105], v[88:89], v[80:81]
	v_mov_b32_e32 v85, v86
	v_pk_fma_f32 v[80:81], v[108:109], v[84:85], v[80:81]
	v_mov_b32_e32 v86, v83
	v_pk_fma_f32 v[80:81], v[112:113], v[86:87], v[80:81]
	s_nop 0
	v_add_f32_e32 v0, v0, v80
	v_add_f32_e32 v0, v0, v81
	v_min_f32_e32 v79, 0, v0
	v_mul_f32_e64 v0, |v0|, s2
	v_exp_f32_e32 v0, v0
	s_nop 0
	v_add_f32_e32 v0, 1.0, v0
	v_cmp_gt_f32_e32 vcc, s33, v0
	s_nop 1
	v_cndmask_b32_e64 v80, 0, 32, vcc
	v_ldexp_f32 v0, v0, v80
	v_log_f32_e32 v0, v0
	s_nop 0
	v_mul_f32_e32 v80, 0x3f317217, v0
	v_fma_f32 v80, v0, s3, -v80
	v_fmac_f32_e32 v80, 0x3377d1cf, v0
	v_fmac_f32_e32 v80, 0x3f317217, v0
	v_cmp_lt_f32_e64 s[0:1], |v0|, s69
	s_nop 1
	v_cndmask_b32_e64 v0, v0, v80, s[0:1]
	v_cndmask_b32_e32 v80, 0, v223, vcc
	v_sub_f32_e32 v0, v0, v80
	ds_read_b128 v[80:83], v168 offset:896
	ds_read_b128 v[84:87], v168 offset:912
	v_sub_f32_e32 v0, v79, v0
	v_fmamk_f32 v79, v0, 0x3d800000, v78
	s_waitcnt lgkmcnt(1)
	v_mov_b32_e32 v88, v80
	s_waitcnt lgkmcnt(0)
	v_mov_b32_e32 v89, v84
	v_mov_b32_e32 v84, v81
	v_pk_mul_f32 v[80:81], v[100:101], v[84:85]
	v_mov_b32_e32 v84, v82
	v_pk_fma_f32 v[80:81], v[98:99], v[88:89], v[80:81]
	v_mov_b32_e32 v85, v86
	v_pk_fma_f32 v[80:81], v[102:103], v[84:85], v[80:81]
	v_mov_b32_e32 v86, v83
	v_pk_fma_f32 v[80:81], v[110:111], v[86:87], v[80:81]
	s_nop 0
	v_add_f32_e32 v0, v165, v80
	v_add_f32_e32 v0, v0, v81
	ds_read_b128 v[80:83], v168 offset:928
	ds_read_b128 v[84:87], v168 offset:944
	s_waitcnt lgkmcnt(1)
	v_mov_b32_e32 v88, v80
	s_waitcnt lgkmcnt(0)
	v_mov_b32_e32 v89, v84
	v_mov_b32_e32 v84, v81
	v_pk_mul_f32 v[80:81], v[106:107], v[84:85]
	v_mov_b32_e32 v84, v82
	v_pk_fma_f32 v[80:81], v[104:105], v[88:89], v[80:81]
	v_mov_b32_e32 v85, v86
	v_pk_fma_f32 v[80:81], v[108:109], v[84:85], v[80:81]
	v_mov_b32_e32 v86, v83
	v_pk_fma_f32 v[80:81], v[112:113], v[86:87], v[80:81]
	ds_read_b128 v[82:85], v168 offset:960
	ds_read_b128 v[86:89], v168 offset:976
	v_add_f32_e32 v0, v0, v80
	v_add_f32_e32 v0, v0, v81
	v_min_f32_e32 v80, 0, v0
	v_mul_f32_e64 v0, |v0|, s2
	v_exp_f32_e32 v0, v0
	s_waitcnt lgkmcnt(0)
	v_mov_b32_e32 v91, v86
	v_mov_b32_e32 v86, v83
	v_mov_b32_e32 v90, v82
	v_add_f32_e32 v0, 1.0, v0
	v_cmp_gt_f32_e32 vcc, s33, v0
	v_pk_mul_f32 v[82:83], v[100:101], v[86:87]
	v_mov_b32_e32 v86, v84
	v_cndmask_b32_e64 v81, 0, 32, vcc
	v_ldexp_f32 v0, v0, v81
	v_log_f32_e32 v0, v0
	v_pk_fma_f32 v[82:83], v[98:99], v[90:91], v[82:83]
	v_mov_b32_e32 v87, v88
	v_pk_fma_f32 v[82:83], v[102:103], v[86:87], v[82:83]
	v_mul_f32_e32 v81, 0x3f317217, v0
	v_fma_f32 v81, v0, s3, -v81
	v_fmac_f32_e32 v81, 0x3377d1cf, v0
	v_fmac_f32_e32 v81, 0x3f317217, v0
	v_cmp_lt_f32_e64 s[0:1], |v0|, s69
	v_mov_b32_e32 v88, v85
	v_pk_fma_f32 v[82:83], v[110:111], v[88:89], v[82:83]
	v_cndmask_b32_e64 v0, v0, v81, s[0:1]
	v_cndmask_b32_e32 v81, 0, v223, vcc
	v_sub_f32_e32 v0, v0, v81
	v_sub_f32_e32 v0, v80, v0
	v_fmamk_f32 v81, v0, 0x3d800000, v79
	v_add_f32_e32 v0, v165, v82
	v_add_f32_e32 v0, v0, v83
	ds_read_b128 v[82:85], v168 offset:992
	ds_read_b128 v[86:89], v168 offset:1008
	s_waitcnt lgkmcnt(1)
	v_mov_b32_e32 v90, v82
	s_waitcnt lgkmcnt(0)
	v_mov_b32_e32 v91, v86
	v_mov_b32_e32 v86, v83
	v_pk_mul_f32 v[82:83], v[106:107], v[86:87]
	v_mov_b32_e32 v86, v84
	v_pk_fma_f32 v[82:83], v[104:105], v[90:91], v[82:83]
	v_mov_b32_e32 v87, v88
	v_pk_fma_f32 v[82:83], v[108:109], v[86:87], v[82:83]
	v_mov_b32_e32 v88, v85
	v_pk_fma_f32 v[82:83], v[112:113], v[88:89], v[82:83]
	s_nop 0
	v_add_f32_e32 v0, v0, v82
	v_add_f32_e32 v0, v0, v83
	v_min_f32_e32 v80, 0, v0
	v_mul_f32_e64 v0, |v0|, s2
	v_exp_f32_e32 v0, v0
	s_nop 0
	v_add_f32_e32 v0, 1.0, v0
	v_cmp_gt_f32_e32 vcc, s33, v0
	s_nop 1
	v_cndmask_b32_e64 v82, 0, 32, vcc
	v_ldexp_f32 v0, v0, v82
	v_log_f32_e32 v0, v0
	s_nop 0
	v_mul_f32_e32 v82, 0x3f317217, v0
	v_fma_f32 v82, v0, s3, -v82
	v_fmac_f32_e32 v82, 0x3377d1cf, v0
	v_fmac_f32_e32 v82, 0x3f317217, v0
	v_cmp_lt_f32_e64 s[0:1], |v0|, s69
	s_nop 1
	v_cndmask_b32_e64 v0, v0, v82, s[0:1]
	v_cndmask_b32_e32 v82, 0, v223, vcc
	v_sub_f32_e32 v0, v0, v82
	v_sub_f32_e32 v0, v80, v0
	v_fmamk_f32 v82, v0, 0x3d800000, v81
	ds_write_b32 v169, v82 offset:4096
	s_waitcnt lgkmcnt(0)
	s_barrier
	v_add_u32_e32 v90, s62, v171
	v_ashrrev_i32_e32 v91, 31, v90
	v_lshlrev_b64 v[90:91], 11, v[90:91]
	v_lshl_add_u64 v[90:91], v[114:115], 0, v[90:91]
	global_load_ushort v128, v[90:91], off
	global_load_ushort v144, v[90:91], off offset:1024
	v_or_b32_e32 v92, 1, v171
	v_add_u32_e32 v92, s62, v92
	v_ashrrev_i32_e32 v93, 31, v92
	v_lshlrev_b64 v[92:93], 11, v[92:93]
	v_lshl_add_u64 v[92:93], v[114:115], 0, v[92:93]
	global_load_ushort v129, v[92:93], off
	global_load_ushort v145, v[92:93], off offset:1024
	v_or_b32_e32 v90, 2, v171
	v_add_u32_e32 v90, s62, v90
	v_ashrrev_i32_e32 v91, 31, v90
	v_lshlrev_b64 v[90:91], 11, v[90:91]
	v_lshl_add_u64 v[90:91], v[114:115], 0, v[90:91]
	global_load_ushort v130, v[90:91], off
	global_load_ushort v146, v[90:91], off offset:1024
	v_or_b32_e32 v92, 3, v171
	v_add_u32_e32 v92, s62, v92
	v_ashrrev_i32_e32 v93, 31, v92
	v_lshlrev_b64 v[92:93], 11, v[92:93]
	v_lshl_add_u64 v[92:93], v[114:115], 0, v[92:93]
	global_load_ushort v131, v[92:93], off
	global_load_ushort v147, v[92:93], off offset:1024
	v_or_b32_e32 v90, 4, v171
	v_add_u32_e32 v90, s62, v90
	v_ashrrev_i32_e32 v91, 31, v90
	v_lshlrev_b64 v[90:91], 11, v[90:91]
	v_lshl_add_u64 v[90:91], v[114:115], 0, v[90:91]
	global_load_ushort v132, v[90:91], off
	global_load_ushort v148, v[90:91], off offset:1024
	v_or_b32_e32 v92, 5, v171
	v_add_u32_e32 v92, s62, v92
	v_ashrrev_i32_e32 v93, 31, v92
	v_lshlrev_b64 v[92:93], 11, v[92:93]
	v_lshl_add_u64 v[92:93], v[114:115], 0, v[92:93]
	global_load_ushort v133, v[92:93], off
	global_load_ushort v149, v[92:93], off offset:1024
	v_or_b32_e32 v90, 6, v171
	v_add_u32_e32 v90, s62, v90
	v_ashrrev_i32_e32 v91, 31, v90
	v_lshlrev_b64 v[90:91], 11, v[90:91]
	v_lshl_add_u64 v[90:91], v[114:115], 0, v[90:91]
	global_load_ushort v134, v[90:91], off
	global_load_ushort v150, v[90:91], off offset:1024
	v_or_b32_e32 v92, 7, v171
	v_add_u32_e32 v92, s62, v92
	v_ashrrev_i32_e32 v93, 31, v92
	v_lshlrev_b64 v[92:93], 11, v[92:93]
	v_lshl_add_u64 v[92:93], v[114:115], 0, v[92:93]
	global_load_ushort v135, v[92:93], off
	global_load_ushort v151, v[92:93], off offset:1024
	v_or_b32_e32 v90, 8, v171
	v_add_u32_e32 v90, s62, v90
	v_ashrrev_i32_e32 v91, 31, v90
	v_lshlrev_b64 v[90:91], 11, v[90:91]
	v_lshl_add_u64 v[90:91], v[114:115], 0, v[90:91]
	global_load_ushort v136, v[90:91], off
	global_load_ushort v152, v[90:91], off offset:1024
	v_or_b32_e32 v92, 9, v171
	v_add_u32_e32 v92, s62, v92
	v_ashrrev_i32_e32 v93, 31, v92
	v_lshlrev_b64 v[92:93], 11, v[92:93]
	v_lshl_add_u64 v[92:93], v[114:115], 0, v[92:93]
	global_load_ushort v137, v[92:93], off
	global_load_ushort v153, v[92:93], off offset:1024
	v_or_b32_e32 v90, 10, v171
	v_add_u32_e32 v90, s62, v90
	v_ashrrev_i32_e32 v91, 31, v90
	v_lshlrev_b64 v[90:91], 11, v[90:91]
	v_lshl_add_u64 v[90:91], v[114:115], 0, v[90:91]
	global_load_ushort v138, v[90:91], off
	global_load_ushort v154, v[90:91], off offset:1024
	v_or_b32_e32 v92, 11, v171
	v_add_u32_e32 v92, s62, v92
	v_ashrrev_i32_e32 v93, 31, v92
	v_lshlrev_b64 v[92:93], 11, v[92:93]
	v_lshl_add_u64 v[92:93], v[114:115], 0, v[92:93]
	global_load_ushort v139, v[92:93], off
	global_load_ushort v155, v[92:93], off offset:1024
	v_or_b32_e32 v90, 12, v171
	v_add_u32_e32 v90, s62, v90
	v_ashrrev_i32_e32 v91, 31, v90
	v_lshlrev_b64 v[90:91], 11, v[90:91]
	v_lshl_add_u64 v[90:91], v[114:115], 0, v[90:91]
	global_load_ushort v140, v[90:91], off
	global_load_ushort v156, v[90:91], off offset:1024
	v_or_b32_e32 v92, 13, v171
	v_add_u32_e32 v92, s62, v92
	v_ashrrev_i32_e32 v93, 31, v92
	v_lshlrev_b64 v[92:93], 11, v[92:93]
	v_lshl_add_u64 v[92:93], v[114:115], 0, v[92:93]
	global_load_ushort v141, v[92:93], off
	global_load_ushort v157, v[92:93], off offset:1024
	v_or_b32_e32 v90, 14, v171
	v_add_u32_e32 v90, s62, v90
	v_ashrrev_i32_e32 v91, 31, v90
	v_lshlrev_b64 v[90:91], 11, v[90:91]
	v_lshl_add_u64 v[90:91], v[114:115], 0, v[90:91]
	global_load_ushort v142, v[90:91], off
	global_load_ushort v158, v[90:91], off offset:1024
	v_or_b32_e32 v92, 15, v171
	v_add_u32_e32 v92, s62, v92
	v_ashrrev_i32_e32 v93, 31, v92
	v_lshlrev_b64 v[92:93], 11, v[92:93]
	v_lshl_add_u64 v[92:93], v[114:115], 0, v[92:93]
	global_load_ushort v143, v[92:93], off
	global_load_ushort v159, v[92:93], off offset:1024
	v_or_b32_e32 v90, s62, v164
	v_ashrrev_i32_e32 v91, 31, v90
	v_lshlrev_b64 v[90:91], 11, v[90:91]
	v_lshl_add_u64 v[90:91], s[48:49], 0, v[90:91]
	v_lshl_add_u64 v[92:93], v[120:121], 1, v[90:91]
	global_load_dwordx4 v[226:229], v[92:93], off
	v_lshl_add_u64 v[92:93], v[122:123], 1, v[90:91]
	global_load_dwordx4 v[230:233], v[92:93], off
	v_lshl_add_u64 v[92:93], v[124:125], 1, v[90:91]
	global_load_dwordx4 v[234:237], v[92:93], off
	v_lshl_add_u64 v[92:93], v[126:127], 1, v[90:91]
	global_load_dwordx4 v[94:97], v[92:93], off
	ds_read2st64_b32 v[84:85], v170 offset0:16 offset1:18
	s_waitcnt lgkmcnt(0)
	v_add_f32_e32 v0, 0, v84
	v_cndmask_b32_e64 v80, 0, v0, s[14:15]
	v_add_f32_e32 v0, v0, v85
	v_add_f32_e32 v83, v85, v80
	ds_read2st64_b32 v[84:85], v170 offset0:20 offset1:22
	v_cndmask_b32_e64 v80, v80, v83, s[16:17]
	s_waitcnt lgkmcnt(0)
	v_add_f32_e32 v83, v84, v80
	v_add_f32_e32 v0, v0, v84
	v_cndmask_b32_e64 v83, v80, v83, s[18:19]
	v_add_u32_e32 v84, s62, v171
	v_add_f32_e32 v80, v0, v85
	v_add_f32_e32 v0, v85, v83
	v_ashrrev_i32_e32 v85, 31, v84
	v_lshlrev_b64 v[84:85], 11, v[84:85]
	v_lshl_add_u64 v[84:85], v[114:115], 0, v[84:85]
	s_waitcnt vmcnt(4)
	v_mov_b32_e32 v86, v128
	v_cndmask_b32_e64 v83, v83, v0, s[20:21]
	v_add_f32_e32 v66, v66, v83
	v_mul_f32_e32 v66, 0xbfb8aa3b, v66
	v_exp_f32_e32 v66, v66
	v_add_f32_e32 v67, v67, v83
	v_mul_f32_e32 v67, 0xbfb8aa3b, v67
	v_exp_f32_e32 v67, v67
	v_rcp_f32_e32 v87, v66
	v_mul_f32_e32 v0, 0x3fb8aa3b, v80
	v_exp_f32_e32 v0, v0
	v_add_f32_e32 v70, v70, v83
	v_mul_f32_e32 v70, 0xbfb8aa3b, v70
	v_exp_f32_e32 v70, v70
	v_add_f32_e32 v71, v71, v83
	v_mul_f32_e32 v71, 0xbfb8aa3b, v71
	v_exp_f32_e32 v71, v71
	s_waitcnt vmcnt(0)
	v_lshlrev_b32_e32 v86, 16, v86
	v_mul_f32_e32 v86, 0x3db504f3, v86
	v_mul_f32_e32 v86, v86, v87
	v_cvt_pk_bf16_f32 v86, v86, s0
	ds_write_b16 v177, v86 offset:8704
	v_add_u32_e32 v86, s62, v178
	v_ashrrev_i32_e32 v87, 31, v86
	v_lshlrev_b64 v[86:87], 11, v[86:87]
	v_lshl_add_u64 v[86:87], v[114:115], 0, v[86:87]
	v_mov_b32_e32 v84, v144
	s_nop 0
	v_mov_b32_e32 v85, v145
	s_waitcnt vmcnt(1)
	v_lshlrev_b32_e32 v84, 16, v84
	s_waitcnt vmcnt(0)
	v_lshlrev_b32_e32 v85, 16, v85
	v_pk_mul_f32 v[84:85], v[66:67], v[84:85]
	v_rcp_f32_e32 v67, v67
	v_cvt_pk_bf16_f32 v66, v84, s0
	ds_write_b16 v177, v66 offset:26112
	v_mov_b32_e32 v66, v129
	v_pk_mul_f32 v[88:89], v[0:1], v[84:85] op_sel_hi:[0,1]
	s_waitcnt vmcnt(0)
	v_lshlrev_b32_e32 v66, 16, v66
	v_mul_f32_e32 v66, 0x3db504f3, v66
	v_mul_f32_e32 v66, v67, v66
	v_add_f32_e32 v67, v68, v83
	v_or_b32_e32 v68, 2, v171
	v_cvt_pk_bf16_f32 v66, v66, s0
	v_add_u32_e32 v84, s62, v68
	ds_write_b16 v179, v66 offset:8704
	v_cvt_pk_bf16_f32 v66, v85, s0
	v_ashrrev_i32_e32 v85, 31, v84
	v_lshlrev_b64 v[84:85], 11, v[84:85]
	v_lshl_add_u64 v[84:85], v[114:115], 0, v[84:85]
	v_mul_f32_e32 v67, 0xbfb8aa3b, v67
	v_exp_f32_e32 v68, v67
	v_mov_b32_e32 v67, v130
	ds_write_b16 v179, v66 offset:26112
	v_cvt_pk_bf16_f32 v66, v88, v89
	v_rcp_f32_e32 v86, v68
	s_waitcnt vmcnt(0)
	v_lshlrev_b32_e32 v67, 16, v67
	v_mul_f32_e32 v67, 0x3db504f3, v67
	v_mul_f32_e32 v67, v86, v67
	v_cvt_pk_bf16_f32 v67, v67, s0
	ds_write_b16 v180, v67 offset:8704
	v_add_f32_e32 v67, v69, v83
	v_or_b32_e32 v69, 3, v171
	v_add_u32_e32 v86, s62, v69
	v_ashrrev_i32_e32 v87, 31, v86
	v_lshlrev_b64 v[86:87], 11, v[86:87]
	v_mul_f32_e32 v67, 0xbfb8aa3b, v67
	v_lshl_add_u64 v[86:87], v[114:115], 0, v[86:87]
	v_exp_f32_e32 v69, v67
	v_mov_b32_e32 v67, v146
	s_nop 0
	v_mov_b32_e32 v84, v147
	s_waitcnt vmcnt(0)
	v_lshlrev_b32_e32 v85, 16, v84
	v_lshlrev_b32_e32 v84, 16, v67
	v_pk_mul_f32 v[84:85], v[68:69], v[84:85]
	v_rcp_f32_e32 v68, v69
	v_cvt_pk_bf16_f32 v67, v84, s0
	ds_write_b16 v180, v67 offset:26112
	v_mov_b32_e32 v67, v131
	v_pk_mul_f32 v[88:89], v[0:1], v[84:85] op_sel_hi:[0,1]
	s_waitcnt vmcnt(0)
	v_lshlrev_b32_e32 v67, 16, v67
	v_mul_f32_e32 v67, 0x3db504f3, v67
	v_mul_f32_e32 v67, v68, v67
	v_or_b32_e32 v68, 4, v171
	v_add_u32_e32 v68, s62, v68
	v_ashrrev_i32_e32 v69, 31, v68
	v_lshlrev_b64 v[68:69], 11, v[68:69]
	v_lshl_add_u64 v[68:69], v[114:115], 0, v[68:69]
	v_mov_b32_e32 v84, v132
	v_cvt_pk_bf16_f32 v67, v67, s0
	ds_write_b16 v181, v67 offset:8704
	v_cvt_pk_bf16_f32 v67, v85, s0
	v_rcp_f32_e32 v85, v70
	ds_write_b16 v181, v67 offset:26112
	v_cvt_pk_bf16_f32 v67, v88, v89
	s_waitcnt vmcnt(0)
	v_lshlrev_b32_e32 v84, 16, v84
	v_mul_f32_e32 v84, 0x3db504f3, v84
	v_mul_f32_e32 v84, v85, v84
	v_cvt_pk_bf16_f32 v84, v84, s0
	ds_write_b16 v182, v84 offset:8704
	v_or_b32_e32 v84, 5, v171
	v_add_u32_e32 v84, s62, v84
	v_ashrrev_i32_e32 v85, 31, v84
	v_lshlrev_b64 v[84:85], 11, v[84:85]
	v_lshl_add_u64 v[84:85], v[114:115], 0, v[84:85]
	v_mov_b32_e32 v68, v148
	s_nop 0
	v_mov_b32_e32 v69, v149
	s_waitcnt vmcnt(1)
	v_lshlrev_b32_e32 v68, 16, v68
	s_waitcnt vmcnt(0)
	v_lshlrev_b32_e32 v69, 16, v69
	v_pk_mul_f32 v[68:69], v[70:71], v[68:69]
	s_nop 0
	v_cvt_pk_bf16_f32 v70, v68, s0
	v_pk_mul_f32 v[86:87], v[0:1], v[68:69] op_sel_hi:[0,1]
	v_mov_b32_e32 v68, v133
	ds_write_b16 v182, v70 offset:26112
	v_rcp_f32_e32 v70, v71
	s_waitcnt vmcnt(0)
	v_lshlrev_b32_e32 v68, 16, v68
	v_mul_f32_e32 v68, 0x3db504f3, v68
	v_mul_f32_e32 v68, v70, v68
	v_or_b32_e32 v70, 6, v171
	v_add_u32_e32 v70, s62, v70
	v_cvt_pk_bf16_f32 v68, v68, s0
	v_ashrrev_i32_e32 v71, 31, v70
	ds_write_b16 v183, v68 offset:8704
	v_cvt_pk_bf16_f32 v68, v69, s0
	v_add_f32_e32 v69, v73, v83
	v_lshlrev_b64 v[70:71], 11, v[70:71]
	v_lshl_add_u64 v[70:71], v[114:115], 0, v[70:71]
	v_mul_f32_e32 v69, 0xbfb8aa3b, v69
	v_exp_f32_e32 v84, v69
	v_mov_b32_e32 v69, v134
	ds_write_b16 v183, v68 offset:26112
	v_cvt_pk_bf16_f32 v68, v86, v87
	v_rcp_f32_e32 v73, v84
	s_waitcnt vmcnt(0)
	v_lshlrev_b32_e32 v69, 16, v69
	v_mul_f32_e32 v69, 0x3db504f3, v69
	v_mul_f32_e32 v69, v73, v69
	v_or_b32_e32 v73, 7, v171
	v_cvt_pk_bf16_f32 v69, v69, s0
	v_add_u32_e32 v86, s62, v73
	ds_write_b16 v184, v69 offset:8704
	v_add_f32_e32 v69, v75, v83
	v_ashrrev_i32_e32 v87, 31, v86
	v_lshlrev_b64 v[86:87], 11, v[86:87]
	v_mul_f32_e32 v69, 0xbfb8aa3b, v69
	v_lshl_add_u64 v[86:87], v[114:115], 0, v[86:87]
	v_exp_f32_e32 v85, v69
	v_mov_b32_e32 v69, v150
	s_nop 0
	v_mov_b32_e32 v71, v151
	v_add_f32_e32 v73, v76, v83
	v_mul_f32_e32 v73, 0xbfb8aa3b, v73
	s_waitcnt vmcnt(1)
	v_lshlrev_b32_e32 v70, 16, v69
	s_waitcnt vmcnt(0)
	v_lshlrev_b32_e32 v71, 16, v71
	v_pk_mul_f32 v[70:71], v[84:85], v[70:71]
	v_exp_f32_e32 v84, v73
	v_cvt_pk_bf16_f32 v69, v70, s0
	ds_write_b16 v184, v69 offset:26112
	v_mov_b32_e32 v69, v135
	v_pk_mul_f32 v[88:89], v[0:1], v[70:71] op_sel_hi:[0,1]
	v_rcp_f32_e32 v70, v85
	v_rcp_f32_e32 v75, v84
	s_waitcnt vmcnt(0)
	v_lshlrev_b32_e32 v69, 16, v69
	v_mul_f32_e32 v69, 0x3db504f3, v69
	v_mul_f32_e32 v69, v70, v69
	v_or_b32_e32 v70, 8, v171
	v_cvt_pk_bf16_f32 v69, v69, s0
	v_add_u32_e32 v70, s62, v70
	ds_write_b16 v185, v69 offset:8704
	v_cvt_pk_bf16_f32 v69, v71, s0
	v_ashrrev_i32_e32 v71, 31, v70
	v_lshlrev_b64 v[70:71], 11, v[70:71]
	v_lshl_add_u64 v[70:71], v[114:115], 0, v[70:71]
	v_mov_b32_e32 v73, v136
	ds_write_b16 v185, v69 offset:26112
	v_cvt_pk_bf16_f32 v69, v88, v89
	s_waitcnt vmcnt(0)
	v_lshlrev_b32_e32 v73, 16, v73
	v_mul_f32_e32 v73, 0x3db504f3, v73
	v_mul_f32_e32 v73, v75, v73
	v_add_f32_e32 v75, v72, v83
	v_or_b32_e32 v72, 9, v171
	v_cvt_pk_bf16_f32 v73, v73, s0
	v_add_u32_e32 v72, s62, v72
	ds_write_b16 v186, v73 offset:8704
	v_ashrrev_i32_e32 v73, 31, v72
	v_lshlrev_b64 v[72:73], 11, v[72:73]
	v_lshl_add_u64 v[72:73], v[114:115], 0, v[72:73]
	v_mov_b32_e32 v70, v152
	s_nop 0
	v_mov_b32_e32 v71, v153
	v_mul_f32_e32 v75, 0xbfb8aa3b, v75
	v_exp_f32_e32 v85, v75
	s_waitcnt vmcnt(1)
	v_lshlrev_b32_e32 v70, 16, v70
	s_waitcnt vmcnt(0)
	v_lshlrev_b32_e32 v71, 16, v71
	v_pk_mul_f32 v[70:71], v[84:85], v[70:71]
	s_nop 0
	v_cvt_pk_bf16_f32 v75, v70, s0
	v_pk_mul_f32 v[86:87], v[0:1], v[70:71] op_sel_hi:[0,1]
	v_mov_b32_e32 v70, v137
	v_rcp_f32_e32 v72, v85
	ds_write_b16 v186, v75 offset:26112
	s_waitcnt vmcnt(0)
	v_lshlrev_b32_e32 v70, 16, v70
	v_mul_f32_e32 v70, 0x3db504f3, v70
	v_mul_f32_e32 v70, v72, v70
	v_or_b32_e32 v72, 10, v171
	v_add_u32_e32 v72, s62, v72
	v_cvt_pk_bf16_f32 v70, v70, s0
	v_ashrrev_i32_e32 v73, 31, v72
	ds_write_b16 v187, v70 offset:8704
	v_cvt_pk_bf16_f32 v70, v71, s0
	v_add_f32_e32 v71, v74, v83
	v_lshlrev_b64 v[72:73], 11, v[72:73]
	v_lshl_add_u64 v[72:73], v[114:115], 0, v[72:73]
	v_mul_f32_e32 v71, 0xbfb8aa3b, v71
	v_exp_f32_e32 v74, v71
	v_mov_b32_e32 v71, v138
	ds_write_b16 v187, v70 offset:26112
	v_cvt_pk_bf16_f32 v70, v86, v87
	v_rcp_f32_e32 v75, v74
	s_waitcnt vmcnt(0)
	v_lshlrev_b32_e32 v71, 16, v71
	v_mul_f32_e32 v71, 0x3db504f3, v71
	v_mul_f32_e32 v71, v75, v71
	v_or_b32_e32 v75, 11, v171
	v_cvt_pk_bf16_f32 v71, v71, s0
	v_add_u32_e32 v76, s62, v75
	ds_write_b16 v188, v71 offset:8704
	v_add_f32_e32 v71, v77, v83
	v_ashrrev_i32_e32 v77, 31, v76
	v_lshlrev_b64 v[76:77], 11, v[76:77]
	v_mul_f32_e32 v71, 0xbfb8aa3b, v71
	v_lshl_add_u64 v[76:77], v[114:115], 0, v[76:77]
	v_exp_f32_e32 v75, v71
	v_mov_b32_e32 v71, v154
	s_nop 0
	v_mov_b32_e32 v73, v155
	s_waitcnt vmcnt(1)
	v_lshlrev_b32_e32 v72, 16, v71
	s_waitcnt vmcnt(0)
	v_lshlrev_b32_e32 v73, 16, v73
	v_pk_mul_f32 v[72:73], v[74:75], v[72:73]
	v_add_f32_e32 v74, v78, v83
	v_cvt_pk_bf16_f32 v71, v72, s0
	ds_write_b16 v188, v71 offset:26112
	v_mov_b32_e32 v71, v139
	v_pk_mul_f32 v[84:85], v[0:1], v[72:73] op_sel_hi:[0,1]
	v_rcp_f32_e32 v72, v75
	v_mul_f32_e32 v74, 0xbfb8aa3b, v74
	v_exp_f32_e32 v74, v74
	v_rcp_f32_e32 v76, v74
	s_waitcnt vmcnt(0)
	v_lshlrev_b32_e32 v71, 16, v71
	v_mul_f32_e32 v71, 0x3db504f3, v71
	v_mul_f32_e32 v71, v72, v71
	v_or_b32_e32 v72, 12, v171
	v_cvt_pk_bf16_f32 v71, v71, s0
	v_add_u32_e32 v72, s62, v72
	ds_write_b16 v189, v71 offset:8704
	v_cvt_pk_bf16_f32 v71, v73, s0
	v_ashrrev_i32_e32 v73, 31, v72
	v_lshlrev_b64 v[72:73], 11, v[72:73]
	v_lshl_add_u64 v[72:73], v[114:115], 0, v[72:73]
	v_mov_b32_e32 v75, v140
	ds_write_b16 v189, v71 offset:26112
	v_cvt_pk_bf16_f32 v71, v84, v85
	s_waitcnt vmcnt(0)
	v_lshlrev_b32_e32 v75, 16, v75
	v_mul_f32_e32 v75, 0x3db504f3, v75
	v_mul_f32_e32 v75, v76, v75
	v_or_b32_e32 v76, 13, v171
	v_add_u32_e32 v76, s62, v76
	v_cvt_pk_bf16_f32 v75, v75, s0
	v_ashrrev_i32_e32 v77, 31, v76
	ds_write_b16 v190, v75 offset:8704
	v_lshlrev_b64 v[76:77], 11, v[76:77]
	v_lshl_add_u64 v[76:77], v[114:115], 0, v[76:77]
	v_mov_b32_e32 v72, v156
	s_nop 0
	v_mov_b32_e32 v73, v157
	v_add_f32_e32 v75, v79, v83
	v_mul_f32_e32 v75, 0xbfb8aa3b, v75
	v_exp_f32_e32 v75, v75
	s_waitcnt vmcnt(1)
	v_lshlrev_b32_e32 v72, 16, v72
	s_waitcnt vmcnt(0)
	v_lshlrev_b32_e32 v73, 16, v73
	v_pk_mul_f32 v[72:73], v[74:75], v[72:73]
	s_nop 0
	v_cvt_pk_bf16_f32 v74, v72, s0
	v_pk_mul_f32 v[78:79], v[0:1], v[72:73] op_sel_hi:[0,1]
	v_mov_b32_e32 v72, v141
	ds_write_b16 v190, v74 offset:26112
	v_rcp_f32_e32 v74, v75
	s_waitcnt vmcnt(0)
	v_lshlrev_b32_e32 v72, 16, v72
	v_mul_f32_e32 v72, 0x3db504f3, v72
	v_mul_f32_e32 v72, v74, v72
	v_or_b32_e32 v74, 14, v171
	v_add_u32_e32 v74, s62, v74
	v_cvt_pk_bf16_f32 v72, v72, s0
	v_ashrrev_i32_e32 v75, 31, v74
	ds_write_b16 v191, v72 offset:8704
	v_cvt_pk_bf16_f32 v72, v73, s0
	v_add_f32_e32 v73, v81, v83
	v_lshlrev_b64 v[74:75], 11, v[74:75]
	v_lshl_add_u64 v[76:77], v[114:115], 0, v[74:75]
	v_mul_f32_e32 v73, 0xbfb8aa3b, v73
	v_exp_f32_e32 v74, v73
	v_mov_b32_e32 v73, v142
	ds_write_b16 v191, v72 offset:26112
	v_cvt_pk_bf16_f32 v72, v78, v79
	v_rcp_f32_e32 v75, v74
	s_waitcnt vmcnt(0)
	v_lshlrev_b32_e32 v73, 16, v73
	v_mul_f32_e32 v73, 0x3db504f3, v73
	v_mul_f32_e32 v73, v75, v73
	v_or_b32_e32 v75, 15, v171
	v_cvt_pk_bf16_f32 v73, v73, s0
	v_add_u32_e32 v78, s62, v75
	ds_write_b16 v192, v73 offset:8704
	v_add_f32_e32 v73, v83, v82
	v_ashrrev_i32_e32 v79, 31, v78
	v_lshlrev_b64 v[78:79], 11, v[78:79]
	v_mul_f32_e32 v73, 0xbfb8aa3b, v73
	v_lshl_add_u64 v[82:83], v[114:115], 0, v[78:79]
	v_exp_f32_e32 v75, v73
	v_mov_b32_e32 v73, v158
	s_nop 0
	v_mov_b32_e32 v77, v159
	s_waitcnt vmcnt(1)
	v_lshlrev_b32_e32 v76, 16, v73
	s_waitcnt vmcnt(0)
	v_lshlrev_b32_e32 v77, 16, v77
	v_pk_mul_f32 v[76:77], v[74:75], v[76:77]
	s_nop 0
	v_pk_mul_f32 v[78:79], v[0:1], v[76:77] op_sel_hi:[0,1]
	v_mov_b32_e32 v0, v143
	v_cvt_pk_bf16_f32 v73, v76, s0
	ds_write_b16 v192, v73 offset:26112
	v_rcp_f32_e32 v73, v75
	s_waitcnt vmcnt(0)
	v_lshlrev_b32_e32 v0, 16, v0
	v_mul_f32_e32 v0, 0x3db504f3, v0
	v_mul_f32_e32 v0, v73, v0
	v_cvt_pk_bf16_f32 v0, v0, s0
	ds_write_b16 v193, v0 offset:8704
	v_cvt_pk_bf16_f32 v0, v77, s0
	ds_write_b16 v193, v0 offset:26112
	v_cvt_pk_bf16_f32 v73, v78, v79
	ds_write_b128 v210, v[66:69] offset:43520
	ds_write_b128 v210, v[70:73] offset:43536
	s_and_saveexec_b64 s[0:1], s[10:11]
	ds_write_b32 v170, v80 offset:6144
	s_or_b64 exec, exec, s[0:1]
	v_or_b32_e32 v66, s62, v164
	v_ashrrev_i32_e32 v67, 31, v66
	v_lshlrev_b64 v[66:67], 11, v[66:67]
	v_lshl_add_u64 v[70:71], s[48:49], 0, v[66:67]
	v_lshl_add_u64 v[66:67], v[120:121], 1, v[70:71]
	v_mov_b32_e32 v66, v226
	v_mov_b32_e32 v67, v227
	v_mov_b32_e32 v68, v228
	v_mov_b32_e32 v69, v229
	s_andn2_b64 vcc, exec, s[50:51]
	v_add_u32_e32 v0, s58, v174
	s_waitcnt vmcnt(0)
	ds_write_b16 v211, v66 offset:61952
	ds_write_b16_d16_hi v211, v66 offset:62096
	ds_write_b16 v211, v67 offset:62240
	ds_write_b16_d16_hi v211, v67 offset:62384
	ds_write_b16 v211, v68 offset:62528
	ds_write_b16_d16_hi v211, v68 offset:62672
	ds_write_b16 v211, v69 offset:62816
	ds_write_b16_d16_hi v211, v69 offset:62960
	v_lshl_add_u64 v[66:67], v[122:123], 1, v[70:71]
	v_mov_b32_e32 v66, v230
	v_mov_b32_e32 v67, v231
	v_mov_b32_e32 v68, v232
	v_mov_b32_e32 v69, v233
	s_waitcnt vmcnt(0)
	ds_write_b16 v212, v66 offset:61952
	ds_write_b16_d16_hi v212, v66 offset:62096
	ds_write_b16 v212, v67 offset:62240
	ds_write_b16_d16_hi v212, v67 offset:62384
	ds_write_b16 v212, v68 offset:62528
	ds_write_b16_d16_hi v212, v68 offset:62672
	ds_write_b16 v212, v69 offset:62816
	ds_write_b16_d16_hi v212, v69 offset:62960
	v_lshl_add_u64 v[66:67], v[124:125], 1, v[70:71]
	v_mov_b32_e32 v66, v234
	v_mov_b32_e32 v67, v235
	v_mov_b32_e32 v68, v236
	v_mov_b32_e32 v69, v237
	s_waitcnt vmcnt(0)
	ds_write_b16 v213, v66 offset:61952
	ds_write_b16_d16_hi v213, v66 offset:62096
	ds_write_b16 v213, v67 offset:62240
	ds_write_b16_d16_hi v213, v67 offset:62384
	ds_write_b16 v213, v68 offset:62528
	ds_write_b16_d16_hi v213, v68 offset:62672
	ds_write_b16 v213, v69 offset:62816
	ds_write_b16_d16_hi v213, v69 offset:62960
	v_lshl_add_u64 v[66:67], v[126:127], 1, v[70:71]
	v_mov_b32_e32 v66, v94
	v_mov_b32_e32 v67, v95
	v_mov_b32_e32 v68, v96
	v_mov_b32_e32 v69, v97
	s_waitcnt vmcnt(0)
	ds_write_b16 v214, v66 offset:61952
	ds_write_b16_d16_hi v214, v66 offset:62096
	ds_write_b16 v214, v67 offset:62240
	ds_write_b16_d16_hi v214, v67 offset:62384
	ds_write_b16 v214, v68 offset:62528
	ds_write_b16_d16_hi v214, v68 offset:62672
	ds_write_b16 v214, v69 offset:62816
	ds_write_b16_d16_hi v214, v69 offset:62960
	v_mov_b32_e32 v66, 0
	v_mov_b32_e32 v67, 0
	v_mov_b32_e32 v68, 0
	v_mov_b32_e32 v69, 0
	s_waitcnt lgkmcnt(0)
	s_barrier
	s_cbranch_vccnz .LBB0_46
	ds_read_b128 v[66:69], v0 offset:26112
	ds_read_b128 v[70:73], v244 offset:8704
	s_waitcnt lgkmcnt(0)
	v_mfma_f32_16x16x32_bf16 v[66:69], v[66:69], v[70:73], 0
	ds_read_b128 v[70:73], v0 offset:26176
	ds_read_b128 v[74:77], v244 offset:8768
	s_waitcnt lgkmcnt(0)
	v_mfma_f32_16x16x32_bf16 v[66:69], v[70:73], v[74:77], v[66:69]
	ds_read_b128 v[70:73], v0 offset:26240
	ds_read_b128 v[74:77], v244 offset:8832
	s_waitcnt lgkmcnt(0)
	v_mfma_f32_16x16x32_bf16 v[66:69], v[70:73], v[74:77], v[66:69]
	ds_read_b128 v[70:73], v0 offset:26304
	ds_read_b128 v[74:77], v244 offset:8896
	s_waitcnt lgkmcnt(0)
	v_mfma_f32_16x16x32_bf16 v[66:69], v[70:73], v[74:77], v[66:69]

.LBB0_153:
	s_or_b64 exec, exec, s[0:1]
	v_add_u32_e32 v66, s5, v124
	v_ashrrev_i32_e32 v67, 31, v66
	v_lshlrev_b64 v[66:67], 11, v[66:67]
	v_lshl_add_u64 v[70:71], s[24:25], 0, v[66:67]
	v_lshl_add_u64 v[66:67], v[106:107], 1, v[70:71]
	v_mov_b32_e32 v66, v204
	v_mov_b32_e32 v67, v205
	v_mov_b32_e32 v68, v206
	v_mov_b32_e32 v69, v207
	v_add_u32_e32 v0, 0, v121
	s_mul_i32 s0, s26, 0x1200
	v_add_u32_e32 v133, s0, v122
	s_add_i32 s5, s5, 64
	s_cmpk_eq_i32 s5, 0x100
	s_waitcnt vmcnt(0)
	ds_write_b16 v129, v66 offset:61952
	ds_write_b16_d16_hi v129, v66 offset:62096
	ds_write_b16 v129, v67 offset:62240
	ds_write_b16_d16_hi v129, v67 offset:62384
	ds_write_b16 v129, v68 offset:62528
	ds_write_b16_d16_hi v129, v68 offset:62672
	ds_write_b16 v129, v69 offset:62816
	ds_write_b16_d16_hi v129, v69 offset:62960
	v_lshl_add_u64 v[66:67], v[108:109], 1, v[70:71]
	v_mov_b32_e32 v66, v208
	v_mov_b32_e32 v67, v209
	v_mov_b32_e32 v68, v210
	v_mov_b32_e32 v69, v211
	s_waitcnt vmcnt(0)
	ds_write_b16 v130, v66 offset:61952
	ds_write_b16_d16_hi v130, v66 offset:62096
	ds_write_b16 v130, v67 offset:62240
	ds_write_b16_d16_hi v130, v67 offset:62384
	ds_write_b16 v130, v68 offset:62528
	ds_write_b16_d16_hi v130, v68 offset:62672
	ds_write_b16 v130, v69 offset:62816
	ds_write_b16_d16_hi v130, v69 offset:62960
	v_lshl_add_u64 v[66:67], v[110:111], 1, v[70:71]
	v_mov_b32_e32 v66, v212
	v_mov_b32_e32 v67, v213
	v_mov_b32_e32 v68, v214
	v_mov_b32_e32 v69, v215
	s_waitcnt vmcnt(0)
	ds_write_b16 v131, v66 offset:61952
	ds_write_b16_d16_hi v131, v66 offset:62096
	ds_write_b16 v131, v67 offset:62240
	ds_write_b16_d16_hi v131, v67 offset:62384
	ds_write_b16 v131, v68 offset:62528
	ds_write_b16_d16_hi v131, v68 offset:62672
	ds_write_b16 v131, v69 offset:62816
	ds_write_b16_d16_hi v131, v69 offset:62960
	v_lshl_add_u64 v[66:67], v[112:113], 1, v[70:71]
	v_mov_b32_e32 v66, v226
	v_mov_b32_e32 v67, v227
	v_mov_b32_e32 v68, v228
	v_mov_b32_e32 v69, v229
	s_waitcnt vmcnt(0)
	ds_write_b16 v132, v66 offset:61952
	ds_write_b16_d16_hi v132, v66 offset:62096
	ds_write_b16 v132, v67 offset:62240
	ds_write_b16_d16_hi v132, v67 offset:62384
	ds_write_b16 v132, v68 offset:62528
	ds_write_b16_d16_hi v132, v68 offset:62672
	ds_write_b16 v132, v69 offset:62816
	ds_write_b16_d16_hi v132, v69 offset:62960
	s_waitcnt lgkmcnt(0)
	s_barrier
	ds_read_b128 v[66:69], v0 offset:6144
	ds_read_b128 v[78:81], v122 offset:43520
	ds_read_b128 v[82:85], v122 offset:43584
	ds_read_b128 v[70:73], v133 offset:62016
	s_waitcnt lgkmcnt(3)
	v_mul_f32_e32 v66, 0x3fb8aa3b, v66
	v_exp_f32_e32 v74, v66
	v_mul_f32_e32 v66, 0x3fb8aa3b, v67
	v_exp_f32_e32 v75, v66
	v_mul_f32_e32 v66, 0x3fb8aa3b, v68
	v_exp_f32_e32 v76, v66
	v_mul_f32_e32 v66, 0x3fb8aa3b, v69
	v_exp_f32_e32 v77, v66
	v_pk_mul_f32 v[62:63], v[62:63], v[74:75]
	ds_read_b128 v[66:69], v133 offset:61952
	v_pk_mul_f32 v[58:59], v[58:59], v[74:75]
	v_pk_mul_f32 v[64:65], v[64:65], v[76:77]
	v_pk_mul_f32 v[60:61], v[60:61], v[76:77]
	ds_read_b128 v[74:77], v133 offset:64256
	s_waitcnt lgkmcnt(1)
	v_mfma_f32_16x16x32_bf16 v[62:65], v[78:81], v[66:69], v[62:65]
	s_waitcnt lgkmcnt(0)
	v_mfma_f32_16x16x32_bf16 v[58:61], v[78:81], v[74:77], v[58:61]
	ds_read_b128 v[78:81], v133 offset:64320
	v_mfma_f32_16x16x32_bf16 v[62:65], v[82:85], v[70:73], v[62:65]
	s_waitcnt lgkmcnt(0)
	v_mfma_f32_16x16x32_bf16 v[58:61], v[82:85], v[78:81], v[58:61]
	ds_read_b128 v[82:85], v0 offset:6208
	s_waitcnt lgkmcnt(0)
	v_mul_f32_e32 v82, 0x3fb8aa3b, v82
	v_exp_f32_e32 v138, v82
	v_mul_f32_e32 v82, 0x3fb8aa3b, v83
	v_exp_f32_e32 v139, v82
	v_mul_f32_e32 v82, 0x3fb8aa3b, v84
	v_exp_f32_e32 v140, v82
	v_mul_f32_e32 v82, 0x3fb8aa3b, v85
	v_exp_f32_e32 v141, v82
	ds_read_b128 v[82:85], v122 offset:45824
	ds_read_b128 v[134:137], v122 offset:45888
	v_pk_mul_f32 v[54:55], v[54:55], v[138:139]
	v_pk_mul_f32 v[50:51], v[50:51], v[138:139]
	v_pk_mul_f32 v[56:57], v[56:57], v[140:141]
	v_pk_mul_f32 v[52:53], v[52:53], v[140:141]
	s_waitcnt lgkmcnt(1)
	v_mfma_f32_16x16x32_bf16 v[54:57], v[82:85], v[66:69], v[54:57]
	v_mfma_f32_16x16x32_bf16 v[50:53], v[82:85], v[74:77], v[50:53]
	ds_read_b128 v[82:85], v0 offset:6272
	s_waitcnt lgkmcnt(0)
	v_mul_f32_e32 v82, 0x3fb8aa3b, v82
	v_exp_f32_e32 v138, v82
	v_mul_f32_e32 v82, 0x3fb8aa3b, v83
	v_exp_f32_e32 v139, v82
	v_mul_f32_e32 v82, 0x3fb8aa3b, v84
	v_exp_f32_e32 v140, v82
	v_mul_f32_e32 v82, 0x3fb8aa3b, v85
	v_exp_f32_e32 v141, v82
	v_mfma_f32_16x16x32_bf16 v[54:57], v[134:137], v[70:73], v[54:57]
	v_mul_f32_e64 v46, v46, v138
	v_mul_f32_e64 v47, v47, v139
	v_pk_mul_f32 v[38:39], v[38:39], v[138:139]
	v_pk_mul_f32 v[48:49], v[48:49], v[140:141]
	v_mfma_f32_16x16x32_bf16 v[50:53], v[134:137], v[78:81], v[50:53]
	ds_read_b128 v[82:85], v122 offset:48128
	ds_read_b128 v[134:137], v122 offset:48192
	v_pk_mul_f32 v[40:41], v[40:41], v[140:141]
	s_waitcnt lgkmcnt(1)
	v_mfma_f32_16x16x32_bf16 v[46:49], v[82:85], v[66:69], v[46:49]
	v_mfma_f32_16x16x32_bf16 v[38:41], v[82:85], v[74:77], v[38:41]
	ds_read_b128 v[82:85], v0 offset:6336
	s_waitcnt lgkmcnt(0)
	v_mul_f32_e32 v82, 0x3fb8aa3b, v82
	v_exp_f32_e32 v138, v82
	v_mul_f32_e32 v82, 0x3fb8aa3b, v83
	v_exp_f32_e32 v139, v82
	v_mul_f32_e32 v82, 0x3fb8aa3b, v84
	v_exp_f32_e32 v140, v82
	v_mul_f32_e32 v82, 0x3fb8aa3b, v85
	v_exp_f32_e32 v141, v82
	v_mfma_f32_16x16x32_bf16 v[46:49], v[134:137], v[70:73], v[46:49]
	v_mul_f32_e64 v42, v42, v138
	v_mul_f32_e64 v43, v43, v139
	v_pk_mul_f32 v[34:35], v[34:35], v[138:139]
	v_pk_mul_f32 v[44:45], v[44:45], v[140:141]
	v_mfma_f32_16x16x32_bf16 v[38:41], v[134:137], v[78:81], v[38:41]
	ds_read_b128 v[82:85], v122 offset:50432
	ds_read_b128 v[134:137], v122 offset:50496
	v_pk_mul_f32 v[36:37], v[36:37], v[140:141]
	s_waitcnt lgkmcnt(1)
	v_mfma_f32_16x16x32_bf16 v[42:45], v[82:85], v[66:69], v[42:45]
	v_mfma_f32_16x16x32_bf16 v[34:37], v[82:85], v[74:77], v[34:37]
	ds_read_b128 v[82:85], v0 offset:6400
	s_waitcnt lgkmcnt(0)
	v_mul_f32_e32 v82, 0x3fb8aa3b, v82
	v_exp_f32_e32 v138, v82
	v_mul_f32_e32 v82, 0x3fb8aa3b, v83
	v_exp_f32_e32 v139, v82
	v_mul_f32_e32 v82, 0x3fb8aa3b, v84
	v_exp_f32_e32 v140, v82
	v_mul_f32_e32 v82, 0x3fb8aa3b, v85
	v_exp_f32_e32 v141, v82
	v_mfma_f32_16x16x32_bf16 v[42:45], v[134:137], v[70:73], v[42:45]
	v_mul_f32_e64 v30, v30, v138
	v_mul_f32_e64 v31, v31, v139
	v_pk_mul_f32 v[22:23], v[22:23], v[138:139]
	v_pk_mul_f32 v[32:33], v[32:33], v[140:141]
	v_mfma_f32_16x16x32_bf16 v[34:37], v[134:137], v[78:81], v[34:37]
	ds_read_b128 v[82:85], v122 offset:52736
	ds_read_b128 v[134:137], v122 offset:52800
	v_pk_mul_f32 v[24:25], v[24:25], v[140:141]
	s_waitcnt lgkmcnt(1)
	v_mfma_f32_16x16x32_bf16 v[30:33], v[82:85], v[66:69], v[30:33]
	v_mfma_f32_16x16x32_bf16 v[22:25], v[82:85], v[74:77], v[22:25]
	ds_read_b128 v[82:85], v0 offset:6464
	s_waitcnt lgkmcnt(0)
	v_mul_f32_e32 v82, 0x3fb8aa3b, v82
	v_exp_f32_e32 v138, v82
	v_mul_f32_e32 v82, 0x3fb8aa3b, v83
	v_exp_f32_e32 v139, v82
	v_mul_f32_e32 v82, 0x3fb8aa3b, v84
	v_exp_f32_e32 v140, v82
	v_mul_f32_e32 v82, 0x3fb8aa3b, v85
	v_exp_f32_e32 v141, v82
	v_mfma_f32_16x16x32_bf16 v[30:33], v[134:137], v[70:73], v[30:33]
	v_mul_f32_e64 v26, v26, v138
	v_mul_f32_e64 v27, v27, v139
	v_pk_mul_f32 v[18:19], v[18:19], v[138:139]
	v_pk_mul_f32 v[28:29], v[28:29], v[140:141]
	v_mfma_f32_16x16x32_bf16 v[22:25], v[134:137], v[78:81], v[22:25]
	ds_read_b128 v[82:85], v122 offset:55040
	ds_read_b128 v[134:137], v122 offset:55104
	v_pk_mul_f32 v[20:21], v[20:21], v[140:141]
	s_waitcnt lgkmcnt(1)
	v_mfma_f32_16x16x32_bf16 v[26:29], v[82:85], v[66:69], v[26:29]
	v_mfma_f32_16x16x32_bf16 v[18:21], v[82:85], v[74:77], v[18:21]
	ds_read_b128 v[82:85], v0 offset:6528
	s_waitcnt lgkmcnt(0)
	v_mul_f32_e32 v82, 0x3fb8aa3b, v82
	v_exp_f32_e32 v138, v82
	v_mul_f32_e32 v82, 0x3fb8aa3b, v83
	v_exp_f32_e32 v139, v82
	v_mul_f32_e32 v82, 0x3fb8aa3b, v84
	v_exp_f32_e32 v140, v82
	v_mul_f32_e32 v82, 0x3fb8aa3b, v85
	v_exp_f32_e32 v141, v82
	v_mfma_f32_16x16x32_bf16 v[26:29], v[134:137], v[70:73], v[26:29]
	v_mul_f32_e64 v14, v14, v138
	v_mul_f32_e64 v15, v15, v139
	v_pk_mul_f32 v[6:7], v[6:7], v[138:139]
	v_pk_mul_f32 v[16:17], v[16:17], v[140:141]
	v_mfma_f32_16x16x32_bf16 v[18:21], v[134:137], v[78:81], v[18:21]
	ds_read_b128 v[82:85], v122 offset:57344
	ds_read_b128 v[134:137], v122 offset:57408
	v_pk_mul_f32 v[8:9], v[8:9], v[140:141]
	s_waitcnt lgkmcnt(1)
	v_mfma_f32_16x16x32_bf16 v[14:17], v[82:85], v[66:69], v[14:17]
	v_mfma_f32_16x16x32_bf16 v[6:9], v[82:85], v[74:77], v[6:9]
	ds_read_b128 v[82:85], v0 offset:6592
	s_waitcnt lgkmcnt(0)
	v_mul_f32_e32 v0, 0x3fb8aa3b, v82
	v_exp_f32_e32 v138, v0
	v_mul_f32_e32 v0, 0x3fb8aa3b, v83
	v_exp_f32_e32 v139, v0
	v_mul_f32_e32 v0, 0x3fb8aa3b, v84
	v_exp_f32_e32 v140, v0
	v_mul_f32_e32 v0, 0x3fb8aa3b, v85
	v_exp_f32_e32 v141, v0
	v_mfma_f32_16x16x32_bf16 v[14:17], v[134:137], v[70:73], v[14:17]
	v_mul_f32_e64 v10, v10, v138
	v_mul_f32_e64 v11, v11, v139
	v_pk_mul_f32 v[2:3], v[2:3], v[138:139]
	v_pk_mul_f32 v[12:13], v[12:13], v[140:141]
	v_mfma_f32_16x16x32_bf16 v[6:9], v[134:137], v[78:81], v[6:9]
	ds_read_b128 v[82:85], v122 offset:59648
	ds_read_b128 v[134:137], v122 offset:59712
	v_pk_mul_f32 v[4:5], v[4:5], v[140:141]
	s_waitcnt lgkmcnt(0)
	v_mfma_f32_16x16x32_bf16 v[10:13], v[82:85], v[66:69], v[10:13]
	s_barrier
	v_mfma_f32_16x16x32_bf16 v[2:5], v[82:85], v[74:77], v[2:5]
	v_mfma_f32_16x16x32_bf16 v[10:13], v[134:137], v[70:73], v[10:13]
	v_mfma_f32_16x16x32_bf16 v[2:5], v[134:137], v[78:81], v[2:5]
	s_cbranch_scc1 .LBB0_160

.LBB0_156:
	s_or_b64 exec, exec, s[0:1]
	s_and_saveexec_b64 s[0:1], s[6:7]
	ds_write_b32 v119, v1 offset:6656
	s_or_b64 exec, exec, s[0:1]
	s_waitcnt lgkmcnt(0)
	s_barrier
	ds_read_b128 v[66:69], v118
	ds_read_b128 v[70:73], v118 offset:16
	ds_read_b128 v[74:77], v118 offset:32
	ds_read_b128 v[78:81], v118 offset:48
	s_mov_b32 s23, 0x800000
	s_waitcnt lgkmcnt(3)
	v_mov_b32_e32 v82, v66
	s_waitcnt lgkmcnt(2)
	v_mov_b32_e32 v83, v70
	v_mov_b32_e32 v70, v67
	s_waitcnt vmcnt(6)
	v_pk_mul_f32 v[66:67], v[90:91], v[70:71]
	v_mov_b32_e32 v70, v68
	v_pk_fma_f32 v[66:67], v[88:89], v[82:83], v[66:67]
	v_mov_b32_e32 v71, v72
	v_pk_fma_f32 v[66:67], v[86:87], v[70:71], v[66:67]
	v_mov_b32_e32 v72, v69
	s_waitcnt vmcnt(4)
	v_pk_fma_f32 v[66:67], v[98:99], v[72:73], v[66:67]
	s_waitcnt vmcnt(0)
	v_add_f32_e32 v0, v117, v66
	v_add_f32_e32 v0, v0, v67
	s_waitcnt lgkmcnt(0)
	v_mov_b32_e32 v67, v78
	v_mov_b32_e32 v78, v75
	v_mov_b32_e32 v66, v74
	v_pk_mul_f32 v[68:69], v[94:95], v[78:79]
	s_nop 0
	v_pk_fma_f32 v[66:67], v[92:93], v[66:67], v[68:69]
	v_mov_b32_e32 v68, v76
	v_mov_b32_e32 v69, v80
	v_pk_fma_f32 v[66:67], v[96:97], v[68:69], v[66:67]
	v_mov_b32_e32 v80, v77
	v_pk_fma_f32 v[66:67], v[100:101], v[80:81], v[66:67]
	ds_read_b128 v[68:71], v118 offset:64
	ds_read_b128 v[72:75], v118 offset:80
	v_add_f32_e32 v0, v0, v66
	v_add_f32_e32 v0, v0, v67
	v_min_f32_e32 v66, 0, v0
	v_mul_f32_e64 v0, |v0|, s30
	v_exp_f32_e32 v0, v0
	s_waitcnt lgkmcnt(0)
	v_mov_b32_e32 v77, v72
	v_mov_b32_e32 v72, v69
	v_mov_b32_e32 v76, v68
	v_add_f32_e32 v0, 1.0, v0
	v_cmp_gt_f32_e64 s[0:1], s23, v0
	v_pk_mul_f32 v[68:69], v[90:91], v[72:73]
	v_mov_b32_e32 v72, v70
	v_cndmask_b32_e64 v67, 0, 32, s[0:1]
	v_ldexp_f32 v0, v0, v67
	v_log_f32_e32 v0, v0
	v_pk_fma_f32 v[68:69], v[88:89], v[76:77], v[68:69]
	v_mov_b32_e32 v73, v74
	v_pk_fma_f32 v[68:69], v[86:87], v[72:73], v[68:69]
	v_mul_f32_e32 v67, 0x3f317217, v0
	v_fma_f32 v67, v0, s31, -v67
	v_fmac_f32_e32 v67, 0x3377d1cf, v0
	v_fmac_f32_e32 v67, 0x3f317217, v0
	v_cmp_lt_f32_e64 s[18:19], |v0|, s41
	v_mov_b32_e32 v74, v71
	v_pk_fma_f32 v[68:69], v[98:99], v[74:75], v[68:69]
	v_cndmask_b32_e64 v0, v0, v67, s[18:19]
	v_cndmask_b32_e64 v67, 0, v223, s[0:1]
	v_sub_f32_e32 v0, v0, v67
	v_sub_f32_e32 v0, v66, v0
	s_mov_b32 s0, 0x3d800000
	v_fma_f32 v66, v0, s0, 0
	v_add_f32_e32 v0, v117, v68
	v_add_f32_e32 v0, v0, v69
	ds_read_b128 v[68:71], v118 offset:96
	ds_read_b128 v[72:75], v118 offset:112
	s_waitcnt lgkmcnt(1)
	v_mov_b32_e32 v76, v68
	s_waitcnt lgkmcnt(0)
	v_mov_b32_e32 v77, v72
	v_mov_b32_e32 v72, v69
	v_pk_mul_f32 v[68:69], v[94:95], v[72:73]
	v_mov_b32_e32 v72, v70
	v_pk_fma_f32 v[68:69], v[92:93], v[76:77], v[68:69]
	v_mov_b32_e32 v73, v74
	v_pk_fma_f32 v[68:69], v[96:97], v[72:73], v[68:69]
	v_mov_b32_e32 v74, v71
	v_pk_fma_f32 v[68:69], v[100:101], v[74:75], v[68:69]
	s_nop 0
	v_add_f32_e32 v0, v0, v68
	v_add_f32_e32 v0, v0, v69
	v_min_f32_e32 v67, 0, v0
	v_mul_f32_e64 v0, |v0|, s30
	v_exp_f32_e32 v0, v0
	s_nop 0
	v_add_f32_e32 v0, 1.0, v0
	v_cmp_gt_f32_e64 s[0:1], s23, v0
	s_nop 1
	v_cndmask_b32_e64 v68, 0, 32, s[0:1]
	v_ldexp_f32 v0, v0, v68
	v_log_f32_e32 v0, v0
	s_nop 0
	v_mul_f32_e32 v68, 0x3f317217, v0
	v_fma_f32 v68, v0, s31, -v68
	v_fmac_f32_e32 v68, 0x3377d1cf, v0
	v_fmac_f32_e32 v68, 0x3f317217, v0
	v_cmp_lt_f32_e64 s[18:19], |v0|, s41
	s_nop 1
	v_cndmask_b32_e64 v0, v0, v68, s[18:19]
	v_cndmask_b32_e64 v68, 0, v223, s[0:1]
	v_sub_f32_e32 v0, v0, v68
	ds_read_b128 v[68:71], v118 offset:128
	ds_read_b128 v[72:75], v118 offset:144
	v_sub_f32_e32 v0, v67, v0
	v_fmamk_f32 v67, v0, 0x3d800000, v66
	s_waitcnt lgkmcnt(1)
	v_mov_b32_e32 v76, v68
	s_waitcnt lgkmcnt(0)
	v_mov_b32_e32 v77, v72
	v_mov_b32_e32 v72, v69
	v_pk_mul_f32 v[68:69], v[90:91], v[72:73]
	v_mov_b32_e32 v72, v70
	v_pk_fma_f32 v[68:69], v[88:89], v[76:77], v[68:69]
	v_mov_b32_e32 v73, v74
	v_pk_fma_f32 v[68:69], v[86:87], v[72:73], v[68:69]
	v_mov_b32_e32 v74, v71
	v_pk_fma_f32 v[68:69], v[98:99], v[74:75], v[68:69]
	s_nop 0
	v_add_f32_e32 v0, v117, v68
	v_add_f32_e32 v0, v0, v69
	ds_read_b128 v[68:71], v118 offset:160
	ds_read_b128 v[72:75], v118 offset:176
	s_waitcnt lgkmcnt(1)
	v_mov_b32_e32 v76, v68
	s_waitcnt lgkmcnt(0)
	v_mov_b32_e32 v77, v72
	v_mov_b32_e32 v72, v69
	v_pk_mul_f32 v[68:69], v[94:95], v[72:73]
	v_mov_b32_e32 v72, v70
	v_pk_fma_f32 v[68:69], v[92:93], v[76:77], v[68:69]
	v_mov_b32_e32 v73, v74
	v_pk_fma_f32 v[68:69], v[96:97], v[72:73], v[68:69]
	v_mov_b32_e32 v74, v71
	v_pk_fma_f32 v[68:69], v[100:101], v[74:75], v[68:69]
	ds_read_b128 v[70:73], v118 offset:192
	ds_read_b128 v[74:77], v118 offset:208
	v_add_f32_e32 v0, v0, v68
	v_add_f32_e32 v0, v0, v69
	v_min_f32_e32 v68, 0, v0
	v_mul_f32_e64 v0, |v0|, s30
	v_exp_f32_e32 v0, v0
	s_waitcnt lgkmcnt(0)
	v_mov_b32_e32 v79, v74
	v_mov_b32_e32 v74, v71
	v_mov_b32_e32 v78, v70
	v_add_f32_e32 v0, 1.0, v0
	v_cmp_gt_f32_e64 s[0:1], s23, v0
	v_pk_mul_f32 v[70:71], v[90:91], v[74:75]
	v_mov_b32_e32 v74, v72
	v_cndmask_b32_e64 v69, 0, 32, s[0:1]
	v_ldexp_f32 v0, v0, v69
	v_log_f32_e32 v0, v0
	v_pk_fma_f32 v[70:71], v[88:89], v[78:79], v[70:71]
	v_mov_b32_e32 v75, v76
	v_pk_fma_f32 v[70:71], v[86:87], v[74:75], v[70:71]
	v_mul_f32_e32 v69, 0x3f317217, v0
	v_fma_f32 v69, v0, s31, -v69
	v_fmac_f32_e32 v69, 0x3377d1cf, v0
	v_fmac_f32_e32 v69, 0x3f317217, v0
	v_cmp_lt_f32_e64 s[18:19], |v0|, s41
	v_mov_b32_e32 v76, v73
	v_pk_fma_f32 v[70:71], v[98:99], v[76:77], v[70:71]
	v_cndmask_b32_e64 v0, v0, v69, s[18:19]
	v_cndmask_b32_e64 v69, 0, v223, s[0:1]
	v_sub_f32_e32 v0, v0, v69
	v_sub_f32_e32 v0, v68, v0
	v_fmamk_f32 v68, v0, 0x3d800000, v67
	v_add_f32_e32 v0, v117, v70
	v_add_f32_e32 v0, v0, v71
	ds_read_b128 v[70:73], v118 offset:224
	ds_read_b128 v[74:77], v118 offset:240
	s_waitcnt lgkmcnt(1)
	v_mov_b32_e32 v78, v70
	s_waitcnt lgkmcnt(0)
	v_mov_b32_e32 v79, v74
	v_mov_b32_e32 v74, v71
	v_pk_mul_f32 v[70:71], v[94:95], v[74:75]
	v_mov_b32_e32 v74, v72
	v_pk_fma_f32 v[70:71], v[92:93], v[78:79], v[70:71]
	v_mov_b32_e32 v75, v76
	v_pk_fma_f32 v[70:71], v[96:97], v[74:75], v[70:71]
	v_mov_b32_e32 v76, v73
	v_pk_fma_f32 v[70:71], v[100:101], v[76:77], v[70:71]
	s_nop 0
	v_add_f32_e32 v0, v0, v70
	v_add_f32_e32 v0, v0, v71
	v_min_f32_e32 v69, 0, v0
	v_mul_f32_e64 v0, |v0|, s30
	v_exp_f32_e32 v0, v0
	s_nop 0
	v_add_f32_e32 v0, 1.0, v0
	v_cmp_gt_f32_e64 s[0:1], s23, v0
	s_nop 1
	v_cndmask_b32_e64 v70, 0, 32, s[0:1]
	v_ldexp_f32 v0, v0, v70
	v_log_f32_e32 v0, v0
	s_nop 0
	v_mul_f32_e32 v70, 0x3f317217, v0
	v_fma_f32 v70, v0, s31, -v70
	v_fmac_f32_e32 v70, 0x3377d1cf, v0
	v_fmac_f32_e32 v70, 0x3f317217, v0
	v_cmp_lt_f32_e64 s[18:19], |v0|, s41
	s_nop 1
	v_cndmask_b32_e64 v0, v0, v70, s[18:19]
	v_cndmask_b32_e64 v70, 0, v223, s[0:1]
	v_sub_f32_e32 v0, v0, v70
	ds_read_b128 v[70:73], v118 offset:256
	ds_read_b128 v[74:77], v118 offset:272
	v_sub_f32_e32 v0, v69, v0
	v_fmamk_f32 v69, v0, 0x3d800000, v68
	s_waitcnt lgkmcnt(1)
	v_mov_b32_e32 v78, v70
	s_waitcnt lgkmcnt(0)
	v_mov_b32_e32 v79, v74
	v_mov_b32_e32 v74, v71
	v_pk_mul_f32 v[70:71], v[90:91], v[74:75]
	v_mov_b32_e32 v74, v72
	v_pk_fma_f32 v[70:71], v[88:89], v[78:79], v[70:71]
	v_mov_b32_e32 v75, v76
	v_pk_fma_f32 v[70:71], v[86:87], v[74:75], v[70:71]
	v_mov_b32_e32 v76, v73
	v_pk_fma_f32 v[70:71], v[98:99], v[76:77], v[70:71]
	s_nop 0
	v_add_f32_e32 v0, v117, v70
	v_add_f32_e32 v0, v0, v71
	ds_read_b128 v[70:73], v118 offset:288
	ds_read_b128 v[74:77], v118 offset:304
	s_waitcnt lgkmcnt(1)
	v_mov_b32_e32 v78, v70
	s_waitcnt lgkmcnt(0)
	v_mov_b32_e32 v79, v74
	v_mov_b32_e32 v74, v71
	v_pk_mul_f32 v[70:71], v[94:95], v[74:75]
	v_mov_b32_e32 v74, v72
	v_pk_fma_f32 v[70:71], v[92:93], v[78:79], v[70:71]
	v_mov_b32_e32 v75, v76
	v_pk_fma_f32 v[70:71], v[96:97], v[74:75], v[70:71]
	v_mov_b32_e32 v76, v73
	v_pk_fma_f32 v[70:71], v[100:101], v[76:77], v[70:71]
	ds_read_b128 v[72:75], v118 offset:320
	ds_read_b128 v[76:79], v118 offset:336
	v_add_f32_e32 v0, v0, v70
	v_add_f32_e32 v0, v0, v71
	v_min_f32_e32 v70, 0, v0
	v_mul_f32_e64 v0, |v0|, s30
	v_exp_f32_e32 v0, v0
	s_waitcnt lgkmcnt(0)
	v_mov_b32_e32 v81, v76
	v_mov_b32_e32 v76, v73
	v_mov_b32_e32 v80, v72
	v_add_f32_e32 v0, 1.0, v0
	v_cmp_gt_f32_e64 s[0:1], s23, v0
	v_pk_mul_f32 v[72:73], v[90:91], v[76:77]
	v_mov_b32_e32 v76, v74
	v_cndmask_b32_e64 v71, 0, 32, s[0:1]
	v_ldexp_f32 v0, v0, v71
	v_log_f32_e32 v0, v0
	v_pk_fma_f32 v[72:73], v[88:89], v[80:81], v[72:73]
	v_mov_b32_e32 v77, v78
	v_pk_fma_f32 v[72:73], v[86:87], v[76:77], v[72:73]
	v_mul_f32_e32 v71, 0x3f317217, v0
	v_fma_f32 v71, v0, s31, -v71
	v_fmac_f32_e32 v71, 0x3377d1cf, v0
	v_fmac_f32_e32 v71, 0x3f317217, v0
	v_cmp_lt_f32_e64 s[18:19], |v0|, s41
	v_mov_b32_e32 v78, v75
	v_pk_fma_f32 v[72:73], v[98:99], v[78:79], v[72:73]
	v_cndmask_b32_e64 v0, v0, v71, s[18:19]
	v_cndmask_b32_e64 v71, 0, v223, s[0:1]
	v_sub_f32_e32 v0, v0, v71
	v_sub_f32_e32 v0, v70, v0
	v_fmamk_f32 v70, v0, 0x3d800000, v69
	v_add_f32_e32 v0, v117, v72
	v_add_f32_e32 v0, v0, v73
	ds_read_b128 v[72:75], v118 offset:352
	ds_read_b128 v[76:79], v118 offset:368
	s_waitcnt lgkmcnt(1)
	v_mov_b32_e32 v80, v72
	s_waitcnt lgkmcnt(0)
	v_mov_b32_e32 v81, v76
	v_mov_b32_e32 v76, v73
	v_pk_mul_f32 v[72:73], v[94:95], v[76:77]
	v_mov_b32_e32 v76, v74
	v_pk_fma_f32 v[72:73], v[92:93], v[80:81], v[72:73]
	v_mov_b32_e32 v77, v78
	v_pk_fma_f32 v[72:73], v[96:97], v[76:77], v[72:73]
	v_mov_b32_e32 v78, v75
	v_pk_fma_f32 v[72:73], v[100:101], v[78:79], v[72:73]
	s_nop 0
	v_add_f32_e32 v0, v0, v72
	v_add_f32_e32 v0, v0, v73
	v_min_f32_e32 v71, 0, v0
	v_mul_f32_e64 v0, |v0|, s30
	v_exp_f32_e32 v0, v0
	s_nop 0
	v_add_f32_e32 v0, 1.0, v0
	v_cmp_gt_f32_e64 s[0:1], s23, v0
	s_nop 1
	v_cndmask_b32_e64 v72, 0, 32, s[0:1]
	v_ldexp_f32 v0, v0, v72
	v_log_f32_e32 v0, v0
	s_nop 0
	v_mul_f32_e32 v72, 0x3f317217, v0
	v_fma_f32 v72, v0, s31, -v72
	v_fmac_f32_e32 v72, 0x3377d1cf, v0
	v_fmac_f32_e32 v72, 0x3f317217, v0
	v_cmp_lt_f32_e64 s[18:19], |v0|, s41
	s_nop 1
	v_cndmask_b32_e64 v0, v0, v72, s[18:19]
	v_cndmask_b32_e64 v72, 0, v223, s[0:1]
	v_sub_f32_e32 v0, v0, v72
	ds_read_b128 v[72:75], v118 offset:384
	ds_read_b128 v[76:79], v118 offset:400
	v_sub_f32_e32 v0, v71, v0
	v_fmamk_f32 v71, v0, 0x3d800000, v70
	s_waitcnt lgkmcnt(1)
	v_mov_b32_e32 v80, v72
	s_waitcnt lgkmcnt(0)
	v_mov_b32_e32 v81, v76
	v_mov_b32_e32 v76, v73
	v_pk_mul_f32 v[72:73], v[90:91], v[76:77]
	v_mov_b32_e32 v76, v74
	v_pk_fma_f32 v[72:73], v[88:89], v[80:81], v[72:73]
	v_mov_b32_e32 v77, v78
	v_pk_fma_f32 v[72:73], v[86:87], v[76:77], v[72:73]
	v_mov_b32_e32 v78, v75
	v_pk_fma_f32 v[72:73], v[98:99], v[78:79], v[72:73]
	s_nop 0
	v_add_f32_e32 v0, v117, v72
	v_add_f32_e32 v0, v0, v73
	ds_read_b128 v[72:75], v118 offset:416
	ds_read_b128 v[76:79], v118 offset:432
	s_waitcnt lgkmcnt(1)
	v_mov_b32_e32 v80, v72
	s_waitcnt lgkmcnt(0)
	v_mov_b32_e32 v81, v76
	v_mov_b32_e32 v76, v73
	v_pk_mul_f32 v[72:73], v[94:95], v[76:77]
	v_mov_b32_e32 v76, v74
	v_pk_fma_f32 v[72:73], v[92:93], v[80:81], v[72:73]
	v_mov_b32_e32 v77, v78
	v_pk_fma_f32 v[72:73], v[96:97], v[76:77], v[72:73]
	v_mov_b32_e32 v78, v75
	v_pk_fma_f32 v[72:73], v[100:101], v[78:79], v[72:73]
	ds_read_b128 v[74:77], v118 offset:448
	ds_read_b128 v[78:81], v118 offset:464
	v_add_f32_e32 v0, v0, v72
	v_add_f32_e32 v0, v0, v73
	v_min_f32_e32 v72, 0, v0
	v_mul_f32_e64 v0, |v0|, s30
	v_exp_f32_e32 v0, v0
	s_waitcnt lgkmcnt(0)
	v_mov_b32_e32 v83, v78
	v_mov_b32_e32 v78, v75
	v_mov_b32_e32 v82, v74
	v_add_f32_e32 v0, 1.0, v0
	v_cmp_gt_f32_e64 s[0:1], s23, v0
	v_pk_mul_f32 v[74:75], v[90:91], v[78:79]
	v_mov_b32_e32 v78, v76
	v_cndmask_b32_e64 v73, 0, 32, s[0:1]
	v_ldexp_f32 v0, v0, v73
	v_log_f32_e32 v0, v0
	v_pk_fma_f32 v[74:75], v[88:89], v[82:83], v[74:75]
	v_mov_b32_e32 v79, v80
	v_pk_fma_f32 v[74:75], v[86:87], v[78:79], v[74:75]
	v_mul_f32_e32 v73, 0x3f317217, v0
	v_fma_f32 v73, v0, s31, -v73
	v_fmac_f32_e32 v73, 0x3377d1cf, v0
	v_fmac_f32_e32 v73, 0x3f317217, v0
	v_cmp_lt_f32_e64 s[18:19], |v0|, s41
	v_mov_b32_e32 v80, v77
	v_pk_fma_f32 v[74:75], v[98:99], v[80:81], v[74:75]
	v_cndmask_b32_e64 v0, v0, v73, s[18:19]
	v_cndmask_b32_e64 v73, 0, v223, s[0:1]
	v_sub_f32_e32 v0, v0, v73
	v_sub_f32_e32 v0, v72, v0
	v_fmamk_f32 v72, v0, 0x3d800000, v71
	v_add_f32_e32 v0, v117, v74
	v_add_f32_e32 v0, v0, v75
	ds_read_b128 v[74:77], v118 offset:480
	ds_read_b128 v[78:81], v118 offset:496
	s_waitcnt lgkmcnt(1)
	v_mov_b32_e32 v82, v74
	s_waitcnt lgkmcnt(0)
	v_mov_b32_e32 v83, v78
	v_mov_b32_e32 v78, v75
	v_pk_mul_f32 v[74:75], v[94:95], v[78:79]
	v_mov_b32_e32 v78, v76
	v_pk_fma_f32 v[74:75], v[92:93], v[82:83], v[74:75]
	v_mov_b32_e32 v79, v80
	v_pk_fma_f32 v[74:75], v[96:97], v[78:79], v[74:75]
	v_mov_b32_e32 v80, v77
	v_pk_fma_f32 v[74:75], v[100:101], v[80:81], v[74:75]
	s_nop 0
	v_add_f32_e32 v0, v0, v74
	v_add_f32_e32 v0, v0, v75
	v_min_f32_e32 v73, 0, v0
	v_mul_f32_e64 v0, |v0|, s30
	v_exp_f32_e32 v0, v0
	s_nop 0
	v_add_f32_e32 v0, 1.0, v0
	v_cmp_gt_f32_e64 s[0:1], s23, v0
	s_nop 1
	v_cndmask_b32_e64 v74, 0, 32, s[0:1]
	v_ldexp_f32 v0, v0, v74
	v_log_f32_e32 v0, v0
	s_nop 0
	v_mul_f32_e32 v74, 0x3f317217, v0
	v_fma_f32 v74, v0, s31, -v74
	v_fmac_f32_e32 v74, 0x3377d1cf, v0
	v_fmac_f32_e32 v74, 0x3f317217, v0
	v_cmp_lt_f32_e64 s[18:19], |v0|, s41
	s_nop 1
	v_cndmask_b32_e64 v0, v0, v74, s[18:19]
	v_cndmask_b32_e64 v74, 0, v223, s[0:1]
	v_sub_f32_e32 v0, v0, v74
	ds_read_b128 v[74:77], v118 offset:512
	ds_read_b128 v[78:81], v118 offset:528
	v_sub_f32_e32 v0, v73, v0
	v_fmamk_f32 v73, v0, 0x3d800000, v72
	s_waitcnt lgkmcnt(1)
	v_mov_b32_e32 v82, v74
	s_waitcnt lgkmcnt(0)
	v_mov_b32_e32 v83, v78
	v_mov_b32_e32 v78, v75
	v_pk_mul_f32 v[74:75], v[90:91], v[78:79]
	v_mov_b32_e32 v78, v76
	v_pk_fma_f32 v[74:75], v[88:89], v[82:83], v[74:75]
	v_mov_b32_e32 v79, v80
	v_pk_fma_f32 v[74:75], v[86:87], v[78:79], v[74:75]
	v_mov_b32_e32 v80, v77
	v_pk_fma_f32 v[74:75], v[98:99], v[80:81], v[74:75]
	s_nop 0
	v_add_f32_e32 v0, v117, v74
	v_add_f32_e32 v0, v0, v75
	ds_read_b128 v[74:77], v118 offset:544
	ds_read_b128 v[78:81], v118 offset:560
	s_waitcnt lgkmcnt(1)
	v_mov_b32_e32 v82, v74
	s_waitcnt lgkmcnt(0)
	v_mov_b32_e32 v83, v78
	v_mov_b32_e32 v78, v75
	v_pk_mul_f32 v[74:75], v[94:95], v[78:79]
	v_mov_b32_e32 v78, v76
	v_pk_fma_f32 v[74:75], v[92:93], v[82:83], v[74:75]
	v_mov_b32_e32 v79, v80
	v_pk_fma_f32 v[74:75], v[96:97], v[78:79], v[74:75]
	v_mov_b32_e32 v80, v77
	v_pk_fma_f32 v[74:75], v[100:101], v[80:81], v[74:75]
	ds_read_b128 v[78:81], v118 offset:576
	ds_read_b128 v[82:85], v118 offset:592
	v_add_f32_e32 v0, v0, v74
	v_add_f32_e32 v0, v0, v75
	v_min_f32_e32 v74, 0, v0
	v_mul_f32_e64 v0, |v0|, s30
	v_exp_f32_e32 v0, v0
	s_nop 0
	v_add_f32_e32 v0, 1.0, v0
	v_cmp_gt_f32_e64 s[0:1], s23, v0
	s_nop 1
	v_cndmask_b32_e64 v75, 0, 32, s[0:1]
	v_ldexp_f32 v0, v0, v75
	v_log_f32_e32 v0, v0
	s_nop 0
	v_mul_f32_e32 v75, 0x3f317217, v0
	v_fma_f32 v75, v0, s31, -v75
	v_fmac_f32_e32 v75, 0x3377d1cf, v0
	v_fmac_f32_e32 v75, 0x3f317217, v0
	v_cmp_lt_f32_e64 s[18:19], |v0|, s41
	s_nop 1
	v_cndmask_b32_e64 v0, v0, v75, s[18:19]
	v_cndmask_b32_e64 v75, 0, v223, s[0:1]
	v_sub_f32_e32 v0, v0, v75
	s_waitcnt lgkmcnt(0)
	v_mov_b32_e32 v75, v82
	v_mov_b32_e32 v82, v79
	v_sub_f32_e32 v0, v74, v0
	v_mov_b32_e32 v74, v78
	v_pk_mul_f32 v[78:79], v[90:91], v[82:83]
	v_fmamk_f32 v76, v0, 0x3d800000, v73
	v_pk_fma_f32 v[74:75], v[88:89], v[74:75], v[78:79]
	v_mov_b32_e32 v78, v80
	v_mov_b32_e32 v79, v84
	v_pk_fma_f32 v[74:75], v[86:87], v[78:79], v[74:75]
	v_mov_b32_e32 v84, v81
	v_pk_fma_f32 v[74:75], v[98:99], v[84:85], v[74:75]
	ds_read_b128 v[78:81], v118 offset:608
	ds_read_b128 v[82:85], v118 offset:624
	v_add_f32_e32 v0, v117, v74
	v_add_f32_e32 v0, v0, v75
	s_waitcnt lgkmcnt(1)
	v_mov_b32_e32 v74, v78
	s_waitcnt lgkmcnt(0)
	v_mov_b32_e32 v75, v82
	v_mov_b32_e32 v82, v79
	v_pk_mul_f32 v[78:79], v[94:95], v[82:83]
	s_nop 0
	v_pk_fma_f32 v[74:75], v[92:93], v[74:75], v[78:79]
	v_mov_b32_e32 v78, v80
	v_mov_b32_e32 v79, v84
	v_pk_fma_f32 v[74:75], v[96:97], v[78:79], v[74:75]
	v_mov_b32_e32 v84, v81
	v_pk_fma_f32 v[74:75], v[100:101], v[84:85], v[74:75]
	ds_read_b128 v[78:81], v118 offset:640
	ds_read_b128 v[82:85], v118 offset:656
	v_add_f32_e32 v0, v0, v74
	v_add_f32_e32 v0, v0, v75
	v_min_f32_e32 v74, 0, v0
	v_mul_f32_e64 v0, |v0|, s30
	v_exp_f32_e32 v0, v0
	s_nop 0
	v_add_f32_e32 v0, 1.0, v0
	v_cmp_gt_f32_e64 s[0:1], s23, v0
	s_nop 1
	v_cndmask_b32_e64 v75, 0, 32, s[0:1]
	v_ldexp_f32 v0, v0, v75
	v_log_f32_e32 v0, v0
	s_nop 0
	v_mul_f32_e32 v75, 0x3f317217, v0
	v_fma_f32 v75, v0, s31, -v75
	v_fmac_f32_e32 v75, 0x3377d1cf, v0
	v_fmac_f32_e32 v75, 0x3f317217, v0
	v_cmp_lt_f32_e64 s[18:19], |v0|, s41
	s_nop 1
	v_cndmask_b32_e64 v0, v0, v75, s[18:19]
	v_cndmask_b32_e64 v75, 0, v223, s[0:1]
	v_sub_f32_e32 v0, v0, v75
	s_waitcnt lgkmcnt(0)
	v_mov_b32_e32 v75, v82
	v_mov_b32_e32 v82, v79
	v_sub_f32_e32 v0, v74, v0
	v_mov_b32_e32 v74, v78
	v_pk_mul_f32 v[78:79], v[90:91], v[82:83]
	v_fmamk_f32 v77, v0, 0x3d800000, v76
	v_pk_fma_f32 v[74:75], v[88:89], v[74:75], v[78:79]
	v_mov_b32_e32 v78, v80
	v_mov_b32_e32 v79, v84
	v_pk_fma_f32 v[74:75], v[86:87], v[78:79], v[74:75]
	v_mov_b32_e32 v84, v81
	v_pk_fma_f32 v[74:75], v[98:99], v[84:85], v[74:75]
	ds_read_b128 v[78:81], v118 offset:672
	ds_read_b128 v[82:85], v118 offset:688
	v_add_f32_e32 v0, v117, v74
	v_add_f32_e32 v0, v0, v75
	s_waitcnt lgkmcnt(1)
	v_mov_b32_e32 v74, v78
	s_waitcnt lgkmcnt(0)
	v_mov_b32_e32 v75, v82
	v_mov_b32_e32 v82, v79
	v_pk_mul_f32 v[78:79], v[94:95], v[82:83]
	s_nop 0
	v_pk_fma_f32 v[74:75], v[92:93], v[74:75], v[78:79]
	v_mov_b32_e32 v78, v80
	v_mov_b32_e32 v79, v84
	v_pk_fma_f32 v[74:75], v[96:97], v[78:79], v[74:75]
	v_mov_b32_e32 v84, v81
	v_pk_fma_f32 v[74:75], v[100:101], v[84:85], v[74:75]
	ds_read_b128 v[80:83], v118 offset:704
	ds_read_b128 v[134:137], v118 offset:720
	v_add_f32_e32 v0, v0, v74
	v_add_f32_e32 v0, v0, v75
	v_min_f32_e32 v74, 0, v0
	v_mul_f32_e64 v0, |v0|, s30
	v_exp_f32_e32 v0, v0
	s_nop 0
	v_add_f32_e32 v0, 1.0, v0
	v_cmp_gt_f32_e64 s[0:1], s23, v0
	s_nop 1
	v_cndmask_b32_e64 v75, 0, 32, s[0:1]
	v_ldexp_f32 v0, v0, v75
	v_log_f32_e32 v0, v0
	s_nop 0
	v_mul_f32_e32 v75, 0x3f317217, v0
	v_fma_f32 v75, v0, s31, -v75
	v_fmac_f32_e32 v75, 0x3377d1cf, v0
	v_fmac_f32_e32 v75, 0x3f317217, v0
	v_cmp_lt_f32_e64 s[18:19], |v0|, s41
	s_nop 1
	v_cndmask_b32_e64 v0, v0, v75, s[18:19]
	v_cndmask_b32_e64 v75, 0, v223, s[0:1]
	v_sub_f32_e32 v0, v0, v75
	s_waitcnt lgkmcnt(0)
	v_mov_b32_e32 v75, v134
	v_mov_b32_e32 v134, v81
	v_sub_f32_e32 v0, v74, v0
	v_mov_b32_e32 v74, v80
	v_pk_mul_f32 v[80:81], v[90:91], v[134:135]
	v_fmamk_f32 v78, v0, 0x3d800000, v77
	v_pk_fma_f32 v[74:75], v[88:89], v[74:75], v[80:81]
	v_mov_b32_e32 v80, v82
	v_mov_b32_e32 v81, v136
	v_pk_fma_f32 v[74:75], v[86:87], v[80:81], v[74:75]
	v_mov_b32_e32 v136, v83
	v_pk_fma_f32 v[74:75], v[98:99], v[136:137], v[74:75]
	ds_read_b128 v[80:83], v118 offset:736
	ds_read_b128 v[134:137], v118 offset:752
	v_add_f32_e32 v0, v117, v74
	v_add_f32_e32 v0, v0, v75
	s_waitcnt lgkmcnt(1)
	v_mov_b32_e32 v74, v80
	s_waitcnt lgkmcnt(0)
	v_mov_b32_e32 v75, v134
	v_mov_b32_e32 v134, v81
	v_pk_mul_f32 v[80:81], v[94:95], v[134:135]
	s_nop 0
	v_pk_fma_f32 v[74:75], v[92:93], v[74:75], v[80:81]
	v_mov_b32_e32 v80, v82
	v_mov_b32_e32 v81, v136
	v_pk_fma_f32 v[74:75], v[96:97], v[80:81], v[74:75]
	v_mov_b32_e32 v136, v83
	v_pk_fma_f32 v[74:75], v[100:101], v[136:137], v[74:75]
	ds_read_b128 v[80:83], v118 offset:768
	ds_read_b128 v[134:137], v118 offset:784
	v_add_f32_e32 v0, v0, v74
	v_add_f32_e32 v0, v0, v75
	v_min_f32_e32 v74, 0, v0
	v_mul_f32_e64 v0, |v0|, s30
	v_exp_f32_e32 v0, v0
	s_nop 0
	v_add_f32_e32 v0, 1.0, v0
	v_cmp_gt_f32_e64 s[0:1], s23, v0
	s_nop 1
	v_cndmask_b32_e64 v75, 0, 32, s[0:1]
	v_ldexp_f32 v0, v0, v75
	v_log_f32_e32 v0, v0
	s_nop 0
	v_mul_f32_e32 v75, 0x3f317217, v0
	v_fma_f32 v75, v0, s31, -v75
	v_fmac_f32_e32 v75, 0x3377d1cf, v0
	v_fmac_f32_e32 v75, 0x3f317217, v0
	v_cmp_lt_f32_e64 s[18:19], |v0|, s41
	s_nop 1
	v_cndmask_b32_e64 v0, v0, v75, s[18:19]
	v_cndmask_b32_e64 v75, 0, v223, s[0:1]
	v_sub_f32_e32 v0, v0, v75
	s_waitcnt lgkmcnt(0)
	v_mov_b32_e32 v75, v134
	v_mov_b32_e32 v134, v81
	v_sub_f32_e32 v0, v74, v0
	v_mov_b32_e32 v74, v80
	v_pk_mul_f32 v[80:81], v[90:91], v[134:135]
	v_fmamk_f32 v79, v0, 0x3d800000, v78
	v_pk_fma_f32 v[74:75], v[88:89], v[74:75], v[80:81]
	v_mov_b32_e32 v80, v82
	v_mov_b32_e32 v81, v136
	v_pk_fma_f32 v[74:75], v[86:87], v[80:81], v[74:75]
	v_mov_b32_e32 v136, v83
	v_pk_fma_f32 v[74:75], v[98:99], v[136:137], v[74:75]
	ds_read_b128 v[80:83], v118 offset:800
	ds_read_b128 v[134:137], v118 offset:816
	v_add_f32_e32 v0, v117, v74
	v_add_f32_e32 v0, v0, v75
	s_waitcnt lgkmcnt(1)
	v_mov_b32_e32 v74, v80
	s_waitcnt lgkmcnt(0)
	v_mov_b32_e32 v75, v134
	v_mov_b32_e32 v134, v81
	v_pk_mul_f32 v[80:81], v[94:95], v[134:135]
	s_nop 0
	v_pk_fma_f32 v[74:75], v[92:93], v[74:75], v[80:81]
	v_mov_b32_e32 v80, v82
	v_mov_b32_e32 v81, v136
	v_pk_fma_f32 v[74:75], v[96:97], v[80:81], v[74:75]
	v_mov_b32_e32 v136, v83
	v_pk_fma_f32 v[74:75], v[100:101], v[136:137], v[74:75]
	ds_read_b128 v[82:85], v118 offset:832
	ds_read_b128 v[134:137], v118 offset:848
	v_add_f32_e32 v0, v0, v74
	v_add_f32_e32 v0, v0, v75
	v_min_f32_e32 v74, 0, v0
	v_mul_f32_e64 v0, |v0|, s30
	v_exp_f32_e32 v0, v0
	s_nop 0
	v_add_f32_e32 v0, 1.0, v0
	v_cmp_gt_f32_e64 s[0:1], s23, v0
	s_nop 1
	v_cndmask_b32_e64 v75, 0, 32, s[0:1]
	v_ldexp_f32 v0, v0, v75
	v_log_f32_e32 v0, v0
	s_nop 0
	v_mul_f32_e32 v75, 0x3f317217, v0
	v_fma_f32 v75, v0, s31, -v75
	v_fmac_f32_e32 v75, 0x3377d1cf, v0
	v_fmac_f32_e32 v75, 0x3f317217, v0
	v_cmp_lt_f32_e64 s[18:19], |v0|, s41
	s_nop 1
	v_cndmask_b32_e64 v0, v0, v75, s[18:19]
	v_cndmask_b32_e64 v75, 0, v223, s[0:1]
	v_sub_f32_e32 v0, v0, v75
	s_waitcnt lgkmcnt(0)
	v_mov_b32_e32 v75, v134
	v_mov_b32_e32 v134, v83
	v_sub_f32_e32 v0, v74, v0
	v_mov_b32_e32 v74, v82
	v_pk_mul_f32 v[82:83], v[90:91], v[134:135]
	v_fmamk_f32 v80, v0, 0x3d800000, v79
	v_pk_fma_f32 v[74:75], v[88:89], v[74:75], v[82:83]
	v_mov_b32_e32 v82, v84
	v_mov_b32_e32 v83, v136
	v_pk_fma_f32 v[74:75], v[86:87], v[82:83], v[74:75]
	v_mov_b32_e32 v136, v85
	v_pk_fma_f32 v[74:75], v[98:99], v[136:137], v[74:75]
	ds_read_b128 v[82:85], v118 offset:864
	ds_read_b128 v[134:137], v118 offset:880
	v_add_f32_e32 v0, v117, v74
	v_add_f32_e32 v0, v0, v75
	s_waitcnt lgkmcnt(1)
	v_mov_b32_e32 v74, v82
	s_waitcnt lgkmcnt(0)
	v_mov_b32_e32 v75, v134
	v_mov_b32_e32 v134, v83
	v_pk_mul_f32 v[82:83], v[94:95], v[134:135]
	s_nop 0
	v_pk_fma_f32 v[74:75], v[92:93], v[74:75], v[82:83]
	v_mov_b32_e32 v82, v84
	v_mov_b32_e32 v83, v136
	v_pk_fma_f32 v[74:75], v[96:97], v[82:83], v[74:75]
	v_mov_b32_e32 v136, v85
	v_pk_fma_f32 v[74:75], v[100:101], v[136:137], v[74:75]
	ds_read_b128 v[134:137], v118 offset:896
	ds_read_b128 v[138:141], v118 offset:912
	v_add_f32_e32 v0, v0, v74
	v_add_f32_e32 v0, v0, v75
	v_min_f32_e32 v74, 0, v0
	v_mul_f32_e64 v0, |v0|, s30
	v_exp_f32_e32 v0, v0
	s_nop 0
	v_add_f32_e32 v0, 1.0, v0
	v_cmp_gt_f32_e64 s[0:1], s23, v0
	s_nop 1
	v_cndmask_b32_e64 v75, 0, 32, s[0:1]
	v_ldexp_f32 v0, v0, v75
	v_log_f32_e32 v0, v0
	s_nop 0
	v_mul_f32_e32 v75, 0x3f317217, v0
	v_fma_f32 v75, v0, s31, -v75
	v_fmac_f32_e32 v75, 0x3377d1cf, v0
	v_fmac_f32_e32 v75, 0x3f317217, v0
	v_cmp_lt_f32_e64 s[18:19], |v0|, s41
	s_nop 1
	v_cndmask_b32_e64 v0, v0, v75, s[18:19]
	v_cndmask_b32_e64 v75, 0, v223, s[0:1]
	v_sub_f32_e32 v0, v0, v75
	s_waitcnt lgkmcnt(0)
	v_mov_b32_e32 v75, v138
	v_mov_b32_e32 v138, v135
	v_sub_f32_e32 v0, v74, v0
	v_mov_b32_e32 v74, v134
	v_pk_mul_f32 v[84:85], v[90:91], v[138:139]
	v_fmamk_f32 v82, v0, 0x3d800000, v80
	v_pk_fma_f32 v[74:75], v[88:89], v[74:75], v[84:85]
	v_mov_b32_e32 v84, v136
	v_mov_b32_e32 v85, v140
	v_pk_fma_f32 v[74:75], v[86:87], v[84:85], v[74:75]
	v_mov_b32_e32 v140, v137
	v_pk_fma_f32 v[74:75], v[98:99], v[140:141], v[74:75]
	ds_read_b128 v[134:137], v118 offset:928
	ds_read_b128 v[138:141], v118 offset:944
	v_add_f32_e32 v0, v117, v74
	v_add_f32_e32 v0, v0, v75
	s_waitcnt lgkmcnt(1)
	v_mov_b32_e32 v74, v134
	s_waitcnt lgkmcnt(0)
	v_mov_b32_e32 v75, v138
	v_mov_b32_e32 v138, v135
	v_pk_mul_f32 v[84:85], v[94:95], v[138:139]
	s_nop 0
	v_pk_fma_f32 v[74:75], v[92:93], v[74:75], v[84:85]
	v_mov_b32_e32 v84, v136
	v_mov_b32_e32 v85, v140
	v_pk_fma_f32 v[74:75], v[96:97], v[84:85], v[74:75]
	v_mov_b32_e32 v140, v137
	v_pk_fma_f32 v[74:75], v[100:101], v[140:141], v[74:75]
	ds_read_b128 v[134:137], v118 offset:960
	ds_read_b128 v[138:141], v118 offset:976
	v_add_f32_e32 v0, v0, v74
	v_add_f32_e32 v0, v0, v75
	v_min_f32_e32 v74, 0, v0
	v_mul_f32_e64 v0, |v0|, s30
	v_exp_f32_e32 v0, v0
	s_nop 0
	v_add_f32_e32 v0, 1.0, v0
	v_cmp_gt_f32_e64 s[0:1], s23, v0
	s_nop 1
	v_cndmask_b32_e64 v75, 0, 32, s[0:1]
	v_ldexp_f32 v0, v0, v75
	v_log_f32_e32 v0, v0
	s_nop 0
	v_mul_f32_e32 v75, 0x3f317217, v0
	v_fma_f32 v75, v0, s31, -v75
	v_fmac_f32_e32 v75, 0x3377d1cf, v0
	v_fmac_f32_e32 v75, 0x3f317217, v0
	v_cmp_lt_f32_e64 s[18:19], |v0|, s41
	s_nop 1
	v_cndmask_b32_e64 v0, v0, v75, s[18:19]
	v_cndmask_b32_e64 v75, 0, v223, s[0:1]
	v_sub_f32_e32 v0, v0, v75
	s_waitcnt lgkmcnt(0)
	v_mov_b32_e32 v75, v138
	v_mov_b32_e32 v138, v135
	v_sub_f32_e32 v0, v74, v0
	v_mov_b32_e32 v74, v134
	v_pk_mul_f32 v[84:85], v[90:91], v[138:139]
	v_fmamk_f32 v83, v0, 0x3d800000, v82
	v_pk_fma_f32 v[74:75], v[88:89], v[74:75], v[84:85]
	v_mov_b32_e32 v84, v136
	v_mov_b32_e32 v85, v140
	v_pk_fma_f32 v[74:75], v[86:87], v[84:85], v[74:75]
	v_mov_b32_e32 v140, v137
	v_pk_fma_f32 v[74:75], v[98:99], v[140:141], v[74:75]
	ds_read_b128 v[134:137], v118 offset:992
	ds_read_b128 v[138:141], v118 offset:1008
	v_add_f32_e32 v0, v117, v74
	v_add_f32_e32 v0, v0, v75
	s_waitcnt lgkmcnt(1)
	v_mov_b32_e32 v74, v134
	s_waitcnt lgkmcnt(0)
	v_mov_b32_e32 v75, v138
	v_mov_b32_e32 v138, v135
	v_pk_mul_f32 v[84:85], v[94:95], v[138:139]
	s_nop 0
	v_pk_fma_f32 v[74:75], v[92:93], v[74:75], v[84:85]
	v_mov_b32_e32 v84, v136
	v_mov_b32_e32 v85, v140
	v_pk_fma_f32 v[74:75], v[96:97], v[84:85], v[74:75]
	v_mov_b32_e32 v140, v137
	v_pk_fma_f32 v[74:75], v[100:101], v[140:141], v[74:75]
	s_nop 0
	v_add_f32_e32 v0, v0, v74
	v_add_f32_e32 v0, v0, v75
	v_min_f32_e32 v74, 0, v0
	v_mul_f32_e64 v0, |v0|, s30
	v_exp_f32_e32 v0, v0
	s_nop 0
	v_add_f32_e32 v0, 1.0, v0
	v_cmp_gt_f32_e64 s[0:1], s23, v0
	s_nop 1
	v_cndmask_b32_e64 v75, 0, 32, s[0:1]
	v_ldexp_f32 v0, v0, v75
	v_log_f32_e32 v0, v0
	s_nop 0
	v_mul_f32_e32 v75, 0x3f317217, v0
	v_fma_f32 v75, v0, s31, -v75
	v_fmac_f32_e32 v75, 0x3377d1cf, v0
	v_fmac_f32_e32 v75, 0x3f317217, v0
	v_cmp_lt_f32_e64 s[18:19], |v0|, s41
	s_nop 1
	v_cndmask_b32_e64 v0, v0, v75, s[18:19]
	v_cndmask_b32_e64 v75, 0, v223, s[0:1]
	v_sub_f32_e32 v0, v0, v75
	v_sub_f32_e32 v0, v74, v0
	v_fmamk_f32 v84, v0, 0x3d800000, v83
	ds_write_b32 v119, v84 offset:4096
	s_waitcnt lgkmcnt(0)
	s_barrier
	v_add_u32_e32 v180, s5, v125
	v_mov_b32_e32 v182, v180
	v_ashrrev_i32_e32 v183, 31, v182
	v_lshlrev_b64 v[182:183], 11, v[182:183]
	v_lshl_add_u64 v[182:183], v[102:103], 0, v[182:183]
	global_load_ushort v184, v[182:183], off
	v_add_u32_e32 v182, 1, v180
	v_ashrrev_i32_e32 v183, 31, v182
	v_lshlrev_b64 v[182:183], 11, v[182:183]
	v_lshl_add_u64 v[182:183], v[102:103], 0, v[182:183]
	global_load_ushort v185, v[182:183], off
	v_add_u32_e32 v182, 2, v180
	v_ashrrev_i32_e32 v183, 31, v182
	v_lshlrev_b64 v[182:183], 11, v[182:183]
	v_lshl_add_u64 v[182:183], v[102:103], 0, v[182:183]
	global_load_ushort v186, v[182:183], off
	v_add_u32_e32 v182, 3, v180
	v_ashrrev_i32_e32 v183, 31, v182
	v_lshlrev_b64 v[182:183], 11, v[182:183]
	v_lshl_add_u64 v[182:183], v[102:103], 0, v[182:183]
	global_load_ushort v187, v[182:183], off
	v_add_u32_e32 v182, 4, v180
	v_ashrrev_i32_e32 v183, 31, v182
	v_lshlrev_b64 v[182:183], 11, v[182:183]
	v_lshl_add_u64 v[182:183], v[102:103], 0, v[182:183]
	global_load_ushort v188, v[182:183], off
	v_add_u32_e32 v182, 5, v180
	v_ashrrev_i32_e32 v183, 31, v182
	v_lshlrev_b64 v[182:183], 11, v[182:183]
	v_lshl_add_u64 v[182:183], v[102:103], 0, v[182:183]
	global_load_ushort v189, v[182:183], off
	v_add_u32_e32 v182, 6, v180
	v_ashrrev_i32_e32 v183, 31, v182
	v_lshlrev_b64 v[182:183], 11, v[182:183]
	v_lshl_add_u64 v[182:183], v[102:103], 0, v[182:183]
	global_load_ushort v190, v[182:183], off
	v_add_u32_e32 v182, 7, v180
	v_ashrrev_i32_e32 v183, 31, v182
	v_lshlrev_b64 v[182:183], 11, v[182:183]
	v_lshl_add_u64 v[182:183], v[102:103], 0, v[182:183]
	global_load_ushort v191, v[182:183], off
	v_add_u32_e32 v182, 8, v180
	v_ashrrev_i32_e32 v183, 31, v182
	v_lshlrev_b64 v[182:183], 11, v[182:183]
	v_lshl_add_u64 v[182:183], v[102:103], 0, v[182:183]
	global_load_ushort v192, v[182:183], off
	v_add_u32_e32 v182, 9, v180
	v_ashrrev_i32_e32 v183, 31, v182
	v_lshlrev_b64 v[182:183], 11, v[182:183]
	v_lshl_add_u64 v[182:183], v[102:103], 0, v[182:183]
	global_load_ushort v193, v[182:183], off
	v_add_u32_e32 v182, 10, v180
	v_ashrrev_i32_e32 v183, 31, v182
	v_lshlrev_b64 v[182:183], 11, v[182:183]
	v_lshl_add_u64 v[182:183], v[102:103], 0, v[182:183]
	global_load_ushort v194, v[182:183], off
	v_add_u32_e32 v182, 11, v180
	v_ashrrev_i32_e32 v183, 31, v182
	v_lshlrev_b64 v[182:183], 11, v[182:183]
	v_lshl_add_u64 v[182:183], v[102:103], 0, v[182:183]
	global_load_ushort v195, v[182:183], off
	v_add_u32_e32 v182, 12, v180
	v_ashrrev_i32_e32 v183, 31, v182
	v_lshlrev_b64 v[182:183], 11, v[182:183]
	v_lshl_add_u64 v[182:183], v[102:103], 0, v[182:183]
	global_load_ushort v196, v[182:183], off
	v_add_u32_e32 v182, 13, v180
	v_ashrrev_i32_e32 v183, 31, v182
	v_lshlrev_b64 v[182:183], 11, v[182:183]
	v_lshl_add_u64 v[182:183], v[102:103], 0, v[182:183]
	global_load_ushort v197, v[182:183], off
	v_add_u32_e32 v182, 14, v180
	v_ashrrev_i32_e32 v183, 31, v182
	v_lshlrev_b64 v[182:183], 11, v[182:183]
	v_lshl_add_u64 v[182:183], v[102:103], 0, v[182:183]
	global_load_ushort v198, v[182:183], off
	v_add_u32_e32 v182, 15, v180
	v_ashrrev_i32_e32 v183, 31, v182
	v_lshlrev_b64 v[182:183], 11, v[182:183]
	v_lshl_add_u64 v[182:183], v[102:103], 0, v[182:183]
	global_load_ushort v199, v[182:183], off
	v_add_u32_e32 v182, s5, v124
	v_ashrrev_i32_e32 v183, 31, v182
	v_lshlrev_b64 v[182:183], 11, v[182:183]
	v_lshl_add_u64 v[200:201], s[24:25], 0, v[182:183]
	v_lshl_add_u64 v[182:183], v[106:107], 1, v[200:201]
	global_load_dwordx4 v[204:207], v[182:183], off
	v_lshl_add_u64 v[182:183], v[108:109], 1, v[200:201]
	global_load_dwordx4 v[208:211], v[182:183], off
	v_lshl_add_u64 v[182:183], v[110:111], 1, v[200:201]
	global_load_dwordx4 v[212:215], v[182:183], off
	v_lshl_add_u64 v[182:183], v[112:113], 1, v[200:201]
	global_load_dwordx4 v[226:229], v[182:183], off
	ds_read2st64_b32 v[74:75], v120 offset0:16 offset1:18
	s_waitcnt lgkmcnt(0)
	v_add_f32_e32 v0, 0, v74
	v_cndmask_b32_e64 v74, 0, v0, s[10:11]
	v_add_f32_e32 v0, v0, v75
	v_add_f32_e32 v75, v75, v74
	v_cndmask_b32_e64 v81, v74, v75, s[12:13]
	ds_read2st64_b32 v[74:75], v120 offset0:20 offset1:22
	s_waitcnt lgkmcnt(0)
	v_add_f32_e32 v0, v0, v74
	v_add_f32_e32 v74, v74, v81
	v_cndmask_b32_e64 v74, v81, v74, s[14:15]
	v_add_f32_e32 v81, v0, v75
	v_add_f32_e32 v0, v75, v74
	v_cndmask_b32_e64 v85, v74, v0, s[16:17]
	v_add_u32_e32 v74, s5, v125
	v_ashrrev_i32_e32 v75, 31, v74
	v_add_u32_e32 v136, 1, v74
	v_lshlrev_b64 v[134:135], 11, v[74:75]
	v_ashrrev_i32_e32 v137, 31, v136
	v_lshl_add_u64 v[134:135], v[102:103], 0, v[134:135]
	v_lshlrev_b64 v[136:137], 11, v[136:137]
	v_lshl_add_u64 v[136:137], v[102:103], 0, v[136:137]
	s_waitcnt vmcnt(4)
	v_mov_b32_e32 v75, v184
	v_mov_b32_e32 v133, v185
	v_add_f32_e32 v66, v66, v85
	v_add_f32_e32 v67, v67, v85
	v_mul_f32_e32 v66, 0xbfb8aa3b, v66
	v_mul_f32_e32 v67, 0xbfb8aa3b, v67
	v_mul_f32_e32 v0, 0x3fb8aa3b, v81
	v_exp_f32_e32 v66, v66
	v_exp_f32_e32 v67, v67
	v_exp_f32_e32 v0, v0
	v_add_u32_e32 v136, 3, v74
	v_ashrrev_i32_e32 v137, 31, v136
	v_lshlrev_b64 v[136:137], 11, v[136:137]
	v_lshl_add_u64 v[136:137], v[102:103], 0, v[136:137]
	v_add_f32_e32 v70, v70, v85
	v_add_f32_e32 v71, v71, v85
	v_mul_f32_e32 v70, 0xbfb8aa3b, v70
	v_mul_f32_e32 v71, 0xbfb8aa3b, v71
	v_exp_f32_e32 v70, v70
	v_exp_f32_e32 v71, v71
	s_waitcnt vmcnt(1)
	v_lshlrev_b32_e32 v134, 16, v75
	s_waitcnt vmcnt(0)
	v_lshlrev_b32_e32 v135, 16, v133
	v_pk_mul_f32 v[66:67], v[66:67], v[134:135]
	v_add_u32_e32 v134, 2, v74
	v_pk_mul_f32 v[66:67], v[0:1], v[66:67] op_sel_hi:[0,1]
	v_cvt_pk_bf16_f32 v66, v66, v67
	v_add_f32_e32 v67, v68, v85
	v_ashrrev_i32_e32 v135, 31, v134
	v_mul_f32_e32 v67, 0xbfb8aa3b, v67
	v_lshlrev_b64 v[134:135], 11, v[134:135]
	v_exp_f32_e32 v68, v67
	v_add_f32_e32 v67, v69, v85
	v_lshl_add_u64 v[134:135], v[102:103], 0, v[134:135]
	v_mul_f32_e32 v67, 0xbfb8aa3b, v67
	v_exp_f32_e32 v69, v67
	v_mov_b32_e32 v67, v186
	v_mov_b32_e32 v75, v187
	s_waitcnt vmcnt(1)
	v_lshlrev_b32_e32 v134, 16, v67
	s_waitcnt vmcnt(0)
	v_lshlrev_b32_e32 v135, 16, v75
	v_pk_mul_f32 v[68:69], v[68:69], v[134:135]
	v_add_u32_e32 v134, 5, v74
	v_pk_mul_f32 v[68:69], v[0:1], v[68:69] op_sel_hi:[0,1]
	v_cvt_pk_bf16_f32 v67, v68, v69
	v_add_u32_e32 v68, 4, v74
	v_ashrrev_i32_e32 v69, 31, v68
	v_lshlrev_b64 v[68:69], 11, v[68:69]
	v_ashrrev_i32_e32 v135, 31, v134
	v_lshl_add_u64 v[68:69], v[102:103], 0, v[68:69]
	v_lshlrev_b64 v[134:135], 11, v[134:135]
	v_lshl_add_u64 v[134:135], v[102:103], 0, v[134:135]
	v_mov_b32_e32 v68, v188
	s_nop 0
	v_mov_b32_e32 v69, v189
	v_add_u32_e32 v134, 7, v74
	v_ashrrev_i32_e32 v135, 31, v134
	v_lshlrev_b64 v[134:135], 11, v[134:135]
	v_lshl_add_u64 v[134:135], v[102:103], 0, v[134:135]
	v_add_f32_e32 v75, v80, v85
	v_mul_f32_e32 v75, 0xbfb8aa3b, v75
	s_waitcnt vmcnt(1)
	v_lshlrev_b32_e32 v68, 16, v68
	s_waitcnt vmcnt(0)
	v_lshlrev_b32_e32 v69, 16, v69
	v_pk_mul_f32 v[68:69], v[70:71], v[68:69]
	v_add_u32_e32 v70, 6, v74
	v_pk_mul_f32 v[68:69], v[0:1], v[68:69] op_sel_hi:[0,1]
	v_cvt_pk_bf16_f32 v68, v68, v69
	v_add_f32_e32 v69, v72, v85
	v_ashrrev_i32_e32 v71, 31, v70
	v_mul_f32_e32 v69, 0xbfb8aa3b, v69
	v_lshlrev_b64 v[70:71], 11, v[70:71]
	v_exp_f32_e32 v72, v69
	v_add_f32_e32 v69, v73, v85
	v_lshl_add_u64 v[70:71], v[102:103], 0, v[70:71]
	v_mul_f32_e32 v69, 0xbfb8aa3b, v69
	v_exp_f32_e32 v73, v69
	v_mov_b32_e32 v69, v190
	s_nop 0
	v_mov_b32_e32 v70, v191
	s_waitcnt vmcnt(0)
	v_lshlrev_b32_e32 v71, 16, v70
	v_lshlrev_b32_e32 v70, 16, v69
	v_pk_mul_f32 v[70:71], v[72:73], v[70:71]
	v_add_f32_e32 v72, v76, v85
	v_pk_mul_f32 v[70:71], v[0:1], v[70:71] op_sel_hi:[0,1]
	v_cvt_pk_bf16_f32 v69, v70, v71
	v_add_u32_e32 v70, 8, v74
	v_ashrrev_i32_e32 v71, 31, v70
	v_add_u32_e32 v76, 9, v74
	v_lshlrev_b64 v[70:71], 11, v[70:71]
	v_add_f32_e32 v73, v77, v85
	v_ashrrev_i32_e32 v77, 31, v76
	v_lshl_add_u64 v[70:71], v[102:103], 0, v[70:71]
	v_lshlrev_b64 v[76:77], 11, v[76:77]
	v_lshl_add_u64 v[76:77], v[102:103], 0, v[76:77]
	v_mov_b32_e32 v70, v192
	s_nop 0
	v_mov_b32_e32 v71, v193
	v_mul_f32_e32 v72, 0xbfb8aa3b, v72
	v_mul_f32_e32 v73, 0xbfb8aa3b, v73
	v_exp_f32_e32 v72, v72
	v_exp_f32_e32 v73, v73
	s_waitcnt vmcnt(1)
	v_lshlrev_b32_e32 v70, 16, v70
	s_waitcnt vmcnt(0)
	v_lshlrev_b32_e32 v71, 16, v71
	v_pk_mul_f32 v[70:71], v[72:73], v[70:71]
	v_add_u32_e32 v72, 10, v74
	v_pk_mul_f32 v[70:71], v[0:1], v[70:71] op_sel_hi:[0,1]
	v_cvt_pk_bf16_f32 v70, v70, v71
	v_add_f32_e32 v71, v78, v85
	v_ashrrev_i32_e32 v73, 31, v72
	v_mul_f32_e32 v71, 0xbfb8aa3b, v71
	v_add_u32_e32 v78, 11, v74
	v_lshlrev_b64 v[72:73], 11, v[72:73]
	v_exp_f32_e32 v76, v71
	v_add_f32_e32 v71, v79, v85
	v_ashrrev_i32_e32 v79, 31, v78
	v_lshl_add_u64 v[72:73], v[102:103], 0, v[72:73]
	v_lshlrev_b64 v[78:79], 11, v[78:79]
	v_mul_f32_e32 v71, 0xbfb8aa3b, v71
	v_lshl_add_u64 v[78:79], v[102:103], 0, v[78:79]
	v_exp_f32_e32 v77, v71
	v_mov_b32_e32 v71, v194
	s_nop 0
	v_mov_b32_e32 v72, v195
	v_add_u32_e32 v78, 13, v74
	v_ashrrev_i32_e32 v79, 31, v78
	v_lshlrev_b64 v[78:79], 11, v[78:79]
	v_lshl_add_u64 v[78:79], v[102:103], 0, v[78:79]
	s_waitcnt vmcnt(0)
	v_lshlrev_b32_e32 v73, 16, v72
	v_lshlrev_b32_e32 v72, 16, v71
	v_pk_mul_f32 v[72:73], v[76:77], v[72:73]
	v_exp_f32_e32 v76, v75
	v_pk_mul_f32 v[72:73], v[0:1], v[72:73] op_sel_hi:[0,1]
	v_cvt_pk_bf16_f32 v71, v72, v73
	v_add_u32_e32 v72, 12, v74
	v_ashrrev_i32_e32 v73, 31, v72
	v_lshlrev_b64 v[72:73], 11, v[72:73]
	v_lshl_add_u64 v[72:73], v[102:103], 0, v[72:73]
	v_mov_b32_e32 v72, v196
	s_nop 0
	v_mov_b32_e32 v73, v197
	v_add_f32_e32 v75, v82, v85
	v_mul_f32_e32 v75, 0xbfb8aa3b, v75
	v_exp_f32_e32 v77, v75
	s_waitcnt vmcnt(1)
	v_lshlrev_b32_e32 v72, 16, v72
	s_waitcnt vmcnt(0)
	v_lshlrev_b32_e32 v73, 16, v73
	v_pk_mul_f32 v[72:73], v[76:77], v[72:73]
	v_add_u32_e32 v76, 14, v74
	v_pk_mul_f32 v[72:73], v[0:1], v[72:73] op_sel_hi:[0,1]
	v_cvt_pk_bf16_f32 v72, v72, v73
	v_add_f32_e32 v73, v83, v85
	v_ashrrev_i32_e32 v77, 31, v76
	v_add_u32_e32 v74, 15, v74
	v_lshlrev_b64 v[76:77], 11, v[76:77]
	v_mul_f32_e32 v73, 0xbfb8aa3b, v73
	v_ashrrev_i32_e32 v75, 31, v74
	v_lshl_add_u64 v[78:79], v[102:103], 0, v[76:77]
	v_exp_f32_e32 v76, v73
	v_add_f32_e32 v73, v85, v84
	v_lshlrev_b64 v[74:75], 11, v[74:75]
	v_lshl_add_u64 v[74:75], v[102:103], 0, v[74:75]
	v_mul_f32_e32 v73, 0xbfb8aa3b, v73
	v_exp_f32_e32 v77, v73
	v_mov_b32_e32 v73, v198
	s_nop 0
	v_mov_b32_e32 v74, v199
	s_waitcnt vmcnt(0)
	v_lshlrev_b32_e32 v75, 16, v74
	v_lshlrev_b32_e32 v74, 16, v73
	v_pk_mul_f32 v[74:75], v[76:77], v[74:75]
	s_nop 0
	v_pk_mul_f32 v[74:75], v[0:1], v[74:75] op_sel_hi:[0,1]
	v_cvt_pk_bf16_f32 v73, v74, v75
	ds_write_b128 v127, v[66:69] offset:43520
	ds_write_b128 v127, v[70:73] offset:43536
	s_and_saveexec_b64 s[0:1], s[8:9]
	s_cbranch_execz .LBB0_153
	v_mul_f32_e32 v115, v115, v0
	ds_write_b32 v128, v81 offset:6144
	s_branch .LBB0_153
